# GEMM K-loop heads placed so that each post-barrier MFMA burst starts 16-24 bytes into a 64-byte line (barrier+setprio+waitcnt+first MFMAs in one line)
# baseline (speedup 1.0000x reference)
; template <class Epi, class Sched, bool ALIGN_EPI = false, bool SP2 = false>
; __device__ __forceinline__ void gemm_phase(PG8_LAS unsigned char* lds, const Gemm g, const Sched& S, const Epi& E, const int tid_arg) {
;     ...
;         const bool has_next = S.next(ui + 1, nxt);
;         const char* nA = has_next ? (const char*)g.A + (size_t)nxt.pm * tstep : cA; const char* nB = has_next ? (const char*)g.Bt + (size_t)nxt.pn * tstep : cB;
;     ...
; #pragma unroll
;         for (int a = 0; a < 2; ++a)
; #pragma unroll
;             for (int b = 0; b < 2; ++b)
; #pragma unroll
;                 for (int m = 0; m < 4; ++m)
; #pragma unroll
;                     for (int n = 0; n < 2; ++n) acc[a][b][m][n] = (f32x4){0.f, 0.f, 0.f, 0.f};
;         cur = nxt; cA = nA; cB = nB; ++ui;
.LBB0_95:
	s_ashr_i32 s21, s20, 31
	s_lshl_b64 s[22:23], s[20:21], 19
	s_add_u32 s22, s1, s22
	s_addc_u32 s23, s2, s23
	s_and_b64 s[24:25], s[6:7], exec
	s_cselect_b32 s21, s23, s29
	s_cselect_b32 s45, s22, s28
	s_ashr_i32 s19, s18, 31
	s_lshl_b64 s[24:25], s[18:19], 19
	s_add_u32 s24, s12, s24
	s_addc_u32 s25, s13, s25
	s_and_b64 s[34:35], s[6:7], exec
	s_cselect_b32 s19, s25, s31
	s_cselect_b32 s46, s24, s30
	s_add_u32 s28, s28, 0x40080
	s_addc_u32 s29, s29, 0
	s_add_u32 s47, s30, 0x100
	v_mov_b32_e32 v2, 0
	s_addc_u32 s48, s31, 0
	s_mov_b32 s49, -2
	v_mov_b32_e32 v3, v2
	v_mov_b32_e32 v4, v2
	v_mov_b32_e32 v5, v2
	v_mov_b32_e32 v6, v2
	v_mov_b32_e32 v7, v2
	v_mov_b32_e32 v8, v2
	v_mov_b32_e32 v9, v2
	v_mov_b32_e32 v18, v2
	v_mov_b32_e32 v19, v2
	v_mov_b32_e32 v20, v2
	v_mov_b32_e32 v21, v2
	v_mov_b32_e32 v22, v2
	v_mov_b32_e32 v23, v2
	v_mov_b32_e32 v24, v2
	v_mov_b32_e32 v25, v2
	v_mov_b32_e32 v34, v2
	v_mov_b32_e32 v35, v2
	v_mov_b32_e32 v36, v2
	v_mov_b32_e32 v37, v2
	v_mov_b32_e32 v38, v2
	v_mov_b32_e32 v39, v2
	v_mov_b32_e32 v40, v2
	v_mov_b32_e32 v41, v2
	v_mov_b32_e32 v50, v2
	v_mov_b32_e32 v51, v2
	v_mov_b32_e32 v52, v2
	v_mov_b32_e32 v53, v2
	v_mov_b32_e32 v54, v2
	v_mov_b32_e32 v55, v2
	v_mov_b32_e32 v56, v2
	v_mov_b32_e32 v57, v2
	v_mov_b32_e32 v10, v2
	v_mov_b32_e32 v11, v2
	v_mov_b32_e32 v12, v2
	v_mov_b32_e32 v13, v2
	v_mov_b32_e32 v14, v2
	v_mov_b32_e32 v15, v2
	v_mov_b32_e32 v16, v2
	v_mov_b32_e32 v17, v2
	v_mov_b32_e32 v26, v2
	v_mov_b32_e32 v27, v2
	v_mov_b32_e32 v28, v2
	v_mov_b32_e32 v29, v2
	v_mov_b32_e32 v30, v2
	v_mov_b32_e32 v31, v2
	v_mov_b32_e32 v32, v2
	v_mov_b32_e32 v33, v2
	v_mov_b32_e32 v42, v2
	v_mov_b32_e32 v43, v2
	v_mov_b32_e32 v44, v2
	v_mov_b32_e32 v45, v2
	v_mov_b32_e32 v46, v2
	v_mov_b32_e32 v47, v2
	v_mov_b32_e32 v48, v2
	v_mov_b32_e32 v49, v2
	v_mov_b32_e32 v58, v2
	v_mov_b32_e32 v59, v2
	v_mov_b32_e32 v60, v2
	v_mov_b32_e32 v61, v2
	v_mov_b32_e32 v62, v2
	v_mov_b32_e32 v63, v2
	v_mov_b32_e32 v64, v2
	v_mov_b32_e32 v65, v2
	v_mov_b32_e32 v66, v2
	v_mov_b32_e32 v67, v2
	v_mov_b32_e32 v68, v2
	v_mov_b32_e32 v69, v2
	v_mov_b32_e32 v70, v2
	v_mov_b32_e32 v71, v2
	v_mov_b32_e32 v72, v2
	v_mov_b32_e32 v73, v2
	v_mov_b32_e32 v82, v2
	v_mov_b32_e32 v83, v2
	v_mov_b32_e32 v84, v2
	v_mov_b32_e32 v85, v2
	v_mov_b32_e32 v86, v2
	v_mov_b32_e32 v87, v2
	v_mov_b32_e32 v88, v2
	v_mov_b32_e32 v89, v2
	v_mov_b32_e32 v98, v2
	v_mov_b32_e32 v99, v2
	v_mov_b32_e32 v100, v2
	v_mov_b32_e32 v101, v2
	v_mov_b32_e32 v102, v2
	v_mov_b32_e32 v103, v2
	v_mov_b32_e32 v104, v2
	v_mov_b32_e32 v105, v2
	v_mov_b32_e32 v114, v2
	v_mov_b32_e32 v115, v2
	v_mov_b32_e32 v116, v2
	v_mov_b32_e32 v117, v2
	v_mov_b32_e32 v118, v2
	v_mov_b32_e32 v119, v2
	v_mov_b32_e32 v120, v2
	v_mov_b32_e32 v121, v2
	v_mov_b32_e32 v74, v2
	v_mov_b32_e32 v75, v2
	v_mov_b32_e32 v76, v2
	v_mov_b32_e32 v77, v2
	v_mov_b32_e32 v78, v2
	v_mov_b32_e32 v79, v2
	v_mov_b32_e32 v80, v2
	v_mov_b32_e32 v81, v2
	v_mov_b32_e32 v90, v2
	v_mov_b32_e32 v91, v2
	v_mov_b32_e32 v92, v2
	v_mov_b32_e32 v93, v2
	v_mov_b32_e32 v94, v2
	v_mov_b32_e32 v95, v2
	v_mov_b32_e32 v96, v2
	v_mov_b32_e32 v97, v2
	v_mov_b32_e32 v106, v2
	v_mov_b32_e32 v107, v2
	v_mov_b32_e32 v108, v2
	v_mov_b32_e32 v109, v2
	v_mov_b32_e32 v110, v2
	v_mov_b32_e32 v111, v2
	v_mov_b32_e32 v112, v2
	v_mov_b32_e32 v113, v2
	v_mov_b32_e32 v122, v2
	v_mov_b32_e32 v123, v2
	v_mov_b32_e32 v124, v2
	v_mov_b32_e32 v125, v2
	v_mov_b32_e32 v126, v2
	v_mov_b32_e32 v127, v2
	v_mov_b32_e32 v128, v2
	v_mov_b32_e32 v129, v2
	.p2align 6
	s_nop 0
	s_nop 0
	s_nop 0
	s_nop 0
	s_nop 0
	s_nop 0
	s_nop 0
	s_nop 0
	s_nop 0
	s_nop 0
	s_nop 0

; template <class Epi, class Sched, bool ALIGN_EPI = false, bool SP2 = false>
; __device__ __forceinline__ void gemm_phase(PG8_LAS unsigned char* lds, const Gemm g, const Sched& S, const Epi& E, const int tid_arg) {
;     ...
; #pragma unroll
;         for (int a = 0; a < 2; ++a)
; #pragma unroll
;             for (int b = 0; b < 2; ++b)
; #pragma unroll
;                 for (int m = 0; m < 4; ++m)
; #pragma unroll
;                     for (int n = 0; n < 2; ++n) acc[a][b][m][n] = (f32x4){0.f, 0.f, 0.f, 0.f};
;         cur = nxt; cA = nA; cB = nB; ++ui;
.LBB0_259:
	s_add_u32 s16, s36, 0x100
	v_mov_b32_e32 v2, 0
	s_addc_u32 s31, s37, 0
	s_mov_b32 s56, -2
	s_waitcnt lgkmcnt(0)
	v_mov_b32_e32 v3, v2
	v_mov_b32_e32 v4, v2
	v_mov_b32_e32 v5, v2
	v_mov_b32_e32 v6, v2
	v_mov_b32_e32 v7, v2
	v_mov_b32_e32 v8, v2
	v_mov_b32_e32 v9, v2
	v_mov_b32_e32 v18, v2
	v_mov_b32_e32 v19, v2
	v_mov_b32_e32 v20, v2
	v_mov_b32_e32 v21, v2
	v_mov_b32_e32 v22, v2
	v_mov_b32_e32 v23, v2
	v_mov_b32_e32 v24, v2
	v_mov_b32_e32 v25, v2
	v_mov_b32_e32 v34, v2
	v_mov_b32_e32 v35, v2
	v_mov_b32_e32 v36, v2
	v_mov_b32_e32 v37, v2
	v_mov_b32_e32 v38, v2
	v_mov_b32_e32 v39, v2
	v_mov_b32_e32 v40, v2
	v_mov_b32_e32 v41, v2
	v_mov_b32_e32 v50, v2
	v_mov_b32_e32 v51, v2
	v_mov_b32_e32 v52, v2
	v_mov_b32_e32 v53, v2
	v_mov_b32_e32 v54, v2
	v_mov_b32_e32 v55, v2
	v_mov_b32_e32 v56, v2
	v_mov_b32_e32 v57, v2
	v_mov_b32_e32 v10, v2
	v_mov_b32_e32 v11, v2
	v_mov_b32_e32 v12, v2
	v_mov_b32_e32 v13, v2
	v_mov_b32_e32 v14, v2
	v_mov_b32_e32 v15, v2
	v_mov_b32_e32 v16, v2
	v_mov_b32_e32 v17, v2
	v_mov_b32_e32 v26, v2
	v_mov_b32_e32 v27, v2
	v_mov_b32_e32 v28, v2
	v_mov_b32_e32 v29, v2
	v_mov_b32_e32 v30, v2
	v_mov_b32_e32 v31, v2
	v_mov_b32_e32 v32, v2
	v_mov_b32_e32 v33, v2
	v_mov_b32_e32 v42, v2
	v_mov_b32_e32 v43, v2
	v_mov_b32_e32 v44, v2
	v_mov_b32_e32 v45, v2
	v_mov_b32_e32 v46, v2
	v_mov_b32_e32 v47, v2
	v_mov_b32_e32 v48, v2
	v_mov_b32_e32 v49, v2
	v_mov_b32_e32 v58, v2
	v_mov_b32_e32 v59, v2
	v_mov_b32_e32 v60, v2
	v_mov_b32_e32 v61, v2
	v_mov_b32_e32 v62, v2
	v_mov_b32_e32 v63, v2
	v_mov_b32_e32 v64, v2
	v_mov_b32_e32 v65, v2
	v_mov_b32_e32 v66, v2
	v_mov_b32_e32 v67, v2
	v_mov_b32_e32 v68, v2
	v_mov_b32_e32 v69, v2
	v_mov_b32_e32 v70, v2
	v_mov_b32_e32 v71, v2
	v_mov_b32_e32 v72, v2
	v_mov_b32_e32 v73, v2
	v_mov_b32_e32 v82, v2
	v_mov_b32_e32 v83, v2
	v_mov_b32_e32 v84, v2
	v_mov_b32_e32 v85, v2
	v_mov_b32_e32 v86, v2
	v_mov_b32_e32 v87, v2
	v_mov_b32_e32 v88, v2
	v_mov_b32_e32 v89, v2
	v_mov_b32_e32 v98, v2
	v_mov_b32_e32 v99, v2
	v_mov_b32_e32 v100, v2
	v_mov_b32_e32 v101, v2
	v_mov_b32_e32 v102, v2
	v_mov_b32_e32 v103, v2
	v_mov_b32_e32 v104, v2
	v_mov_b32_e32 v105, v2
	v_mov_b32_e32 v114, v2
	v_mov_b32_e32 v115, v2
	v_mov_b32_e32 v116, v2
	v_mov_b32_e32 v117, v2
	v_mov_b32_e32 v118, v2
	v_mov_b32_e32 v119, v2
	v_mov_b32_e32 v120, v2
	v_mov_b32_e32 v121, v2
	v_mov_b32_e32 v74, v2
	v_mov_b32_e32 v75, v2
	v_mov_b32_e32 v76, v2
	v_mov_b32_e32 v77, v2
	v_mov_b32_e32 v78, v2
	v_mov_b32_e32 v79, v2
	v_mov_b32_e32 v80, v2
	v_mov_b32_e32 v81, v2
	v_mov_b32_e32 v90, v2
	v_mov_b32_e32 v91, v2
	v_mov_b32_e32 v92, v2
	v_mov_b32_e32 v93, v2
	v_mov_b32_e32 v94, v2
	v_mov_b32_e32 v95, v2
	v_mov_b32_e32 v96, v2
	v_mov_b32_e32 v97, v2
	v_mov_b32_e32 v106, v2
	v_mov_b32_e32 v107, v2
	v_mov_b32_e32 v108, v2
	v_mov_b32_e32 v109, v2
	v_mov_b32_e32 v110, v2
	v_mov_b32_e32 v111, v2
	v_mov_b32_e32 v112, v2
	v_mov_b32_e32 v113, v2
	v_mov_b32_e32 v122, v2
	v_mov_b32_e32 v123, v2
	v_mov_b32_e32 v124, v2
	v_mov_b32_e32 v125, v2
	v_mov_b32_e32 v126, v2
	v_mov_b32_e32 v127, v2
	v_mov_b32_e32 v128, v2
	v_mov_b32_e32 v129, v2
	.p2align 6
	s_nop 0
	s_nop 0
	s_nop 0
	s_nop 0
	s_nop 0
	s_nop 0
	s_nop 0
	s_nop 0
	s_nop 0
	s_nop 0
	s_nop 0

; #define PG8_STAGE(bufoff, gbase, voff) do { _Pragma("unroll") for (int _i = 0; _i < 2; ++_i) \
;         __builtin_amdgcn_global_load_lds((const unsigned*)((const char*)(gbase) + (voff)[_i]), (PG8_LAS unsigned*)(lds + (bufoff) + ldsw + _i * 8192), 16, 0, 0); } while (0)
; #define PG8_LDA(dst, b, h) do { _Pragma("unroll") for (int m = 0; m < 4; ++m) _Pragma("unroll") for (int k = 0; k < 2; ++k) dst[m][k] = *(const PG8_LAS bf16x8*)(lds + PG8_SA(b, h) + aoff + m * 2048 + k * 1024); } while (0)
; #define PG8_LDB(dst, b, h) do { _Pragma("unroll") for (int n = 0; n < 2; ++n) _Pragma("unroll") for (int k = 0; k < 2; ++k) dst[n][k] = *(const PG8_LAS bf16x8*)(lds + PG8_SB(b, h) + boff + n * 2048 + k * 1024); } while (0)
; #define PG8_MMA(ai, bj, At, Bt) do { __builtin_amdgcn_s_setprio(1); _Pragma("unroll") for (int m = 0; m < 4; ++m) _Pragma("unroll") for (int n = 0; n < 2; ++n) _Pragma("unroll") for (int k = 0; k < 2; ++k) \
;         acc[ai][bj][m][n] = __builtin_amdgcn_mfma_f32_16x16x32_bf16(Bt[n][k], At[m][k], acc[ai][bj][m][n], 0, 0, 0); __builtin_amdgcn_s_setprio(0); } while (0)
; #define PG8_BAR __builtin_amdgcn_s_barrier()
; template <class Epi, class Sched, bool ALIGN_EPI = false, bool SP2 = false>
; __device__ __forceinline__ void gemm_phase(PG8_LAS unsigned char* lds, const Gemm g, const Sched& S, const Epi& E, const int tid_arg) {
;     ...
;         for (int t = 0; t < nt; t += 2) {
;             const bool last = (t == nt - 2);
;             const char* a1 = cA + (size_t)(t + 1) * kstep;
;             const char* a2 = last ? nA : cA + (size_t)(t + 2) * kstep; const char* b2 = last ? nB : cB + (size_t)(t + 2) * kstep;
;             const char* a3 = a2 + kstep; const char* b3 = b2 + kstep;
;             if (last && has_next) S.a_ready(nxt);
;             if constexpr (SP2) {
;             PG8_LDB(B0, 0, 0); PG8_LDB(B1, 0, 1); PG8_SCHED; PG8_LDA(At, 0, 0); PG8_STAGE(PG8_SA(1, 1), a1 + hstep, voffA);
;             PG8_WAIT_V(8); PG8_WAIT_L(0); PG8_BAR; PG8_MMA(0, 0, At, B0); PG8_MMA(0, 1, At, B1); PG8_BAR; PG8_SCHED;
;     ...
; #pragma unroll
;         for (int a = 0; a < 2; ++a)
; #pragma unroll
;             for (int b = 0; b < 2; ++b)
; #pragma unroll
;                 for (int m = 0; m < 4; ++m)
; #pragma unroll
;                     for (int n = 0; n < 2; ++n) acc[a][b][m][n] = (f32x4){0.f, 0.f, 0.f, 0.f};
;         cur = nxt; cA = nA; cB = nB; ++ui;
.LBB0_362:
	s_ashr_i32 s29, s28, 31
	s_lshl_b64 s[6:7], s[28:29], 19
	s_add_u32 s30, s50, s6
	s_addc_u32 s31, s51, s7
	s_and_b64 s[6:7], s[8:9], exec
	s_cselect_b32 s6, s31, s15
	s_cselect_b32 s7, s30, s14
	s_ashr_i32 s27, s26, 31
	s_lshl_b64 s[34:35], s[26:27], 19
	s_add_u32 s34, s52, s34
	s_addc_u32 s35, s53, s35
	s_and_b64 s[38:39], s[8:9], exec
	s_cselect_b32 s11, s35, s37
	s_cselect_b32 s13, s34, s36
	s_add_u32 s14, s14, 0x40080
	s_addc_u32 s15, s15, 0
	s_add_u32 s27, s36, 0x100
	v_mov_b32_e32 v4, 0
	s_addc_u32 s29, s37, 0
	s_mov_b32 s40, -2
	s_cmp_eq_u32 s10, 32
	s_cselect_b32 s40, 12, -2
	v_mov_b32_e32 v5, v4
	v_mov_b32_e32 v6, v4
	v_mov_b32_e32 v7, v4
	v_mov_b32_e32 v8, v4
	v_mov_b32_e32 v9, v4
	v_mov_b32_e32 v10, v4
	v_mov_b32_e32 v11, v4
	v_mov_b32_e32 v20, v4
	v_mov_b32_e32 v21, v4
	v_mov_b32_e32 v22, v4
	v_mov_b32_e32 v23, v4
	v_mov_b32_e32 v24, v4
	v_mov_b32_e32 v25, v4
	v_mov_b32_e32 v26, v4
	v_mov_b32_e32 v27, v4
	v_mov_b32_e32 v36, v4
	v_mov_b32_e32 v37, v4
	v_mov_b32_e32 v38, v4
	v_mov_b32_e32 v39, v4
	v_mov_b32_e32 v40, v4
	v_mov_b32_e32 v41, v4
	v_mov_b32_e32 v42, v4
	v_mov_b32_e32 v43, v4
	v_mov_b32_e32 v52, v4
	v_mov_b32_e32 v53, v4
	v_mov_b32_e32 v54, v4
	v_mov_b32_e32 v55, v4
	v_mov_b32_e32 v56, v4
	v_mov_b32_e32 v57, v4
	v_mov_b32_e32 v58, v4
	v_mov_b32_e32 v59, v4
	v_mov_b32_e32 v12, v4
	v_mov_b32_e32 v13, v4
	v_mov_b32_e32 v14, v4
	v_mov_b32_e32 v15, v4
	v_mov_b32_e32 v16, v4
	v_mov_b32_e32 v17, v4
	v_mov_b32_e32 v18, v4
	v_mov_b32_e32 v19, v4
	v_mov_b32_e32 v28, v4
	v_mov_b32_e32 v29, v4
	v_mov_b32_e32 v30, v4
	v_mov_b32_e32 v31, v4
	v_mov_b32_e32 v32, v4
	v_mov_b32_e32 v33, v4
	v_mov_b32_e32 v34, v4
	v_mov_b32_e32 v35, v4
	v_mov_b32_e32 v44, v4
	v_mov_b32_e32 v45, v4
	v_mov_b32_e32 v46, v4
	v_mov_b32_e32 v47, v4
	v_mov_b32_e32 v48, v4
	v_mov_b32_e32 v49, v4
	v_mov_b32_e32 v50, v4
	v_mov_b32_e32 v51, v4
	v_mov_b32_e32 v60, v4
	v_mov_b32_e32 v61, v4
	v_mov_b32_e32 v62, v4
	v_mov_b32_e32 v63, v4
	v_mov_b32_e32 v64, v4
	v_mov_b32_e32 v65, v4
	v_mov_b32_e32 v66, v4
	v_mov_b32_e32 v67, v4
	v_mov_b32_e32 v68, v4
	v_mov_b32_e32 v69, v4
	v_mov_b32_e32 v70, v4
	v_mov_b32_e32 v71, v4
	v_mov_b32_e32 v72, v4
	v_mov_b32_e32 v73, v4
	v_mov_b32_e32 v74, v4
	v_mov_b32_e32 v75, v4
	v_mov_b32_e32 v84, v4
	v_mov_b32_e32 v85, v4
	v_mov_b32_e32 v86, v4
	v_mov_b32_e32 v87, v4
	v_mov_b32_e32 v88, v4
	v_mov_b32_e32 v89, v4
	v_mov_b32_e32 v90, v4
	v_mov_b32_e32 v91, v4
	v_mov_b32_e32 v100, v4
	v_mov_b32_e32 v101, v4
	v_mov_b32_e32 v102, v4
	v_mov_b32_e32 v103, v4
	v_mov_b32_e32 v104, v4
	v_mov_b32_e32 v105, v4
	v_mov_b32_e32 v106, v4
	v_mov_b32_e32 v107, v4
	v_mov_b32_e32 v116, v4
	v_mov_b32_e32 v117, v4
	v_mov_b32_e32 v118, v4
	v_mov_b32_e32 v119, v4
	s_waitcnt vmcnt(0)
	v_mov_b32_e32 v120, v4
	v_mov_b32_e32 v121, v4
	v_mov_b32_e32 v122, v4
	v_mov_b32_e32 v123, v4
	v_mov_b32_e32 v76, v4
	v_mov_b32_e32 v77, v4
	v_mov_b32_e32 v78, v4
	v_mov_b32_e32 v79, v4
	v_mov_b32_e32 v80, v4
	v_mov_b32_e32 v81, v4
	v_mov_b32_e32 v82, v4
	v_mov_b32_e32 v83, v4
	v_mov_b32_e32 v92, v4
	v_mov_b32_e32 v93, v4
	v_mov_b32_e32 v94, v4
	v_mov_b32_e32 v95, v4
	v_mov_b32_e32 v96, v4
	v_mov_b32_e32 v97, v4
	v_mov_b32_e32 v98, v4
	v_mov_b32_e32 v99, v4
	v_mov_b32_e32 v108, v4
	v_mov_b32_e32 v109, v4
	v_mov_b32_e32 v110, v4
	v_mov_b32_e32 v111, v4
	v_mov_b32_e32 v112, v4
	v_mov_b32_e32 v113, v4
	v_mov_b32_e32 v114, v4
	v_mov_b32_e32 v115, v4
	v_mov_b32_e32 v124, v4
	v_mov_b32_e32 v125, v4
	v_mov_b32_e32 v126, v4
	v_mov_b32_e32 v127, v4
	v_mov_b32_e32 v128, v4
	v_mov_b32_e32 v129, v4
	v_mov_b32_e32 v130, v4
	v_mov_b32_e32 v131, v4
	.p2align 6
	s_nop 0
	s_nop 0
	s_nop 0
	s_nop 0
	s_nop 0
.LBB0_363:
	s_add_u32 s36, s14, 0xfffc0080
	s_addc_u32 s37, s15, -1
	s_add_i32 s41, 0, 0x10000
	s_cmp_eq_u32 s40, 12
	s_cselect_b32 s39, s6, s37
	s_cselect_b32 s38, s7, s36
	v_add_u32_e32 v2, s41, v167
	s_cselect_b32 s37, s11, s29
	s_cselect_b32 s36, s13, s27
	s_add_i32 s64, 0, 0x14000
	ds_read_b128 v[156:159], v2
	ds_read_b128 v[160:163], v2 offset:1024
	ds_read_b128 v[170:173], v2 offset:2048
	ds_read_b128 v[174:177], v2 offset:3072
	v_add_u32_e32 v2, s64, v167
	ds_read_b128 v[182:185], v2
	ds_read_b128 v[186:189], v2 offset:1024
	ds_read_b128 v[190:193], v2 offset:2048
	ds_read_b128 v[210:213], v2 offset:3072
	v_lshl_add_u64 v[164:165], s[14:15], 0, v[150:151]
	s_add_i32 m0, s55, 0xc000
	ds_read_b128 v[214:217], v169
	ds_read_b128 v[218:221], v169 offset:1024
	ds_read_b128 v[222:225], v169 offset:2048
	ds_read_b128 v[226:229], v169 offset:3072
	ds_read_b128 v[230:233], v169 offset:4096
	ds_read_b128 v[234:237], v169 offset:5120
	ds_read_b128 v[238:241], v169 offset:6144
	ds_read_b128 v[242:245], v169 offset:7168
	global_load_lds_dwordx4 v[164:165], off
	v_lshl_add_u64 v[164:165], s[14:15], 0, v[152:153]
	s_add_i32 m0, s55, 0xe000
	s_nop 0
	global_load_lds_dwordx4 v[164:165], off
	s_waitcnt vmcnt(8)
	s_waitcnt lgkmcnt(0)
	s_barrier
; #define PG8_STAGE(bufoff, gbase, voff) do { _Pragma("unroll") for (int _i = 0; _i < 2; ++_i) \
;         __builtin_amdgcn_global_load_lds((const unsigned*)((const char*)(gbase) + (voff)[_i]), (PG8_LAS unsigned*)(lds + (bufoff) + ldsw + _i * 8192), 16, 0, 0); } while (0)
; #define PG8_LDA(dst, b, h) do { _Pragma("unroll") for (int m = 0; m < 4; ++m) _Pragma("unroll") for (int k = 0; k < 2; ++k) dst[m][k] = *(const PG8_LAS bf16x8*)(lds + PG8_SA(b, h) + aoff + m * 2048 + k * 1024); } while (0)
; #define PG8_MMA(ai, bj, At, Bt) do { __builtin_amdgcn_s_setprio(1); _Pragma("unroll") for (int m = 0; m < 4; ++m) _Pragma("unroll") for (int n = 0; n < 2; ++n) _Pragma("unroll") for (int k = 0; k < 2; ++k) \
;         acc[ai][bj][m][n] = __builtin_amdgcn_mfma_f32_16x16x32_bf16(Bt[n][k], At[m][k], acc[ai][bj][m][n], 0, 0, 0); __builtin_amdgcn_s_setprio(0); } while (0)
; #define PG8_WAIT_V(n) asm volatile("s_waitcnt vmcnt(" #n ")" ::: "memory")
; #define PG8_WAIT_L(n) asm volatile("s_waitcnt lgkmcnt(" #n ")" ::: "memory")
; #define PG8_BAR __builtin_amdgcn_s_barrier()
; #define PG8_SCHED __builtin_amdgcn_sched_barrier(0)
; template <class Epi, class Sched, bool ALIGN_EPI = false, bool SP2 = false>
; __device__ __forceinline__ void gemm_phase(PG8_LAS unsigned char* lds, const Gemm g, const Sched& S, const Epi& E, const int tid_arg) {
;     ...
;             PG8_WAIT_V(8); PG8_WAIT_L(0); PG8_BAR; PG8_MMA(0, 0, At, B0); PG8_MMA(0, 1, At, B1); PG8_BAR; PG8_SCHED;
;             PG8_LDA(At, 0, 1); PG8_STAGE(PG8_SB(0, 0), b2, voffB); PG8_STAGE(PG8_SB(0, 1), b2 + hstep, voffB); PG8_STAGE(PG8_SA(0, 0), a2, voffA);
;             PG8_WAIT_V(8); PG8_WAIT_L(0); PG8_BAR; PG8_MMA(1, 0, At, B0); PG8_MMA(1, 1, At, B1); PG8_BAR; PG8_SCHED;
	s_setprio 1
	s_waitcnt lgkmcnt(0)
	v_mfma_f32_16x16x32_bf16 v[128:131], v[156:159], v[214:217], v[128:131]
	v_mfma_f32_16x16x32_bf16 v[124:127], v[170:173], v[214:217], v[124:127]
	v_mfma_f32_16x16x32_bf16 v[112:115], v[156:159], v[222:225], v[112:115]
	v_mfma_f32_16x16x32_bf16 v[108:111], v[170:173], v[222:225], v[108:111]
	v_mfma_f32_16x16x32_bf16 v[96:99], v[156:159], v[230:233], v[96:99]
	v_mfma_f32_16x16x32_bf16 v[92:95], v[170:173], v[230:233], v[92:95]
	v_mfma_f32_16x16x32_bf16 v[80:83], v[156:159], v[238:241], v[80:83]
	v_mfma_f32_16x16x32_bf16 v[76:79], v[170:173], v[238:241], v[76:79]
	v_mfma_f32_16x16x32_bf16 v[128:131], v[160:163], v[218:221], v[128:131]
	v_mfma_f32_16x16x32_bf16 v[124:127], v[174:177], v[218:221], v[124:127]
	v_mfma_f32_16x16x32_bf16 v[112:115], v[160:163], v[226:229], v[112:115]
	v_mfma_f32_16x16x32_bf16 v[108:111], v[174:177], v[226:229], v[108:111]
	v_mfma_f32_16x16x32_bf16 v[96:99], v[160:163], v[234:237], v[96:99]
	v_mfma_f32_16x16x32_bf16 v[92:95], v[174:177], v[234:237], v[92:95]
	v_mfma_f32_16x16x32_bf16 v[80:83], v[160:163], v[242:245], v[80:83]
	v_mfma_f32_16x16x32_bf16 v[76:79], v[174:177], v[242:245], v[76:79]
	s_setprio 0
	s_setprio 1
	v_mfma_f32_16x16x32_bf16 v[120:123], v[182:185], v[214:217], v[120:123]
	v_mfma_f32_16x16x32_bf16 v[116:119], v[190:193], v[214:217], v[116:119]
	v_mfma_f32_16x16x32_bf16 v[104:107], v[182:185], v[222:225], v[104:107]
	v_mfma_f32_16x16x32_bf16 v[100:103], v[190:193], v[222:225], v[100:103]
	v_mfma_f32_16x16x32_bf16 v[88:91], v[182:185], v[230:233], v[88:91]
	v_mfma_f32_16x16x32_bf16 v[84:87], v[190:193], v[230:233], v[84:87]
	v_mfma_f32_16x16x32_bf16 v[72:75], v[182:185], v[238:241], v[72:75]
	v_mfma_f32_16x16x32_bf16 v[68:71], v[190:193], v[238:241], v[68:71]
	v_mfma_f32_16x16x32_bf16 v[120:123], v[186:189], v[218:221], v[120:123]
	v_mfma_f32_16x16x32_bf16 v[116:119], v[210:213], v[218:221], v[116:119]
	v_mfma_f32_16x16x32_bf16 v[104:107], v[186:189], v[226:229], v[104:107]
	v_mfma_f32_16x16x32_bf16 v[100:103], v[210:213], v[226:229], v[100:103]
	v_mfma_f32_16x16x32_bf16 v[88:91], v[186:189], v[234:237], v[88:91]
	v_mfma_f32_16x16x32_bf16 v[84:87], v[210:213], v[234:237], v[84:87]
	v_mfma_f32_16x16x32_bf16 v[72:75], v[186:189], v[242:245], v[72:75]
	v_mfma_f32_16x16x32_bf16 v[68:71], v[210:213], v[242:245], v[68:71]
	s_setprio 0
	s_barrier
	s_add_i32 s41, s41, s54
	v_lshl_add_u64 v[164:165], s[36:37], 0, v[134:135]
	s_mov_b32 m0, s41
	ds_read_b128 v[214:217], v169 offset:16384
	ds_read_b128 v[218:221], v169 offset:17408
	ds_read_b128 v[222:225], v169 offset:18432
	ds_read_b128 v[226:229], v169 offset:19456
	ds_read_b128 v[230:233], v169 offset:20480
	ds_read_b128 v[234:237], v169 offset:21504
	ds_read_b128 v[238:241], v169 offset:22528
	ds_read_b128 v[242:245], v169 offset:23552
	global_load_lds_dwordx4 v[164:165], off
	s_add_i32 m0, s41, 0x2000
	s_add_u32 s42, s36, 0x40000
	v_lshl_add_u64 v[178:179], s[36:37], 0, v[138:139]
	s_addc_u32 s43, s37, 0
	s_add_i32 s41, s64, s54
	global_load_lds_dwordx4 v[178:179], off
	v_lshl_add_u64 v[194:195], s[42:43], 0, v[134:135]
	s_mov_b32 m0, s41
	v_lshl_add_u64 v[246:247], s[38:39], 0, v[136:137]
	global_load_lds_dwordx4 v[194:195], off
	v_lshl_add_u64 v[194:195], s[42:43], 0, v[138:139]
	s_add_i32 m0, s41, 0x2000
	s_nop 0
	global_load_lds_dwordx4 v[194:195], off
	v_lshl_add_u64 v[194:195], s[38:39], 0, v[132:133]
	s_mov_b32 m0, s55
	s_nop 0
	global_load_lds_dwordx4 v[194:195], off
	s_mov_b32 m0, s56
	s_nop 0
	global_load_lds_dwordx4 v[246:247], off
	s_waitcnt vmcnt(8)
	s_waitcnt lgkmcnt(0)
	s_barrier
	s_setprio 1
	s_waitcnt lgkmcnt(0)
	v_mfma_f32_16x16x32_bf16 v[64:67], v[156:159], v[214:217], v[64:67]
	v_mfma_f32_16x16x32_bf16 v[60:63], v[170:173], v[214:217], v[60:63]
	v_mfma_f32_16x16x32_bf16 v[48:51], v[156:159], v[222:225], v[48:51]
	v_mfma_f32_16x16x32_bf16 v[44:47], v[170:173], v[222:225], v[44:47]
	v_mfma_f32_16x16x32_bf16 v[32:35], v[156:159], v[230:233], v[32:35]
	v_mfma_f32_16x16x32_bf16 v[28:31], v[170:173], v[230:233], v[28:31]
	v_mfma_f32_16x16x32_bf16 v[16:19], v[156:159], v[238:241], v[16:19]
	v_mfma_f32_16x16x32_bf16 v[12:15], v[170:173], v[238:241], v[12:15]
	v_mfma_f32_16x16x32_bf16 v[64:67], v[160:163], v[218:221], v[64:67]
	v_mfma_f32_16x16x32_bf16 v[60:63], v[174:177], v[218:221], v[60:63]
	v_mfma_f32_16x16x32_bf16 v[48:51], v[160:163], v[226:229], v[48:51]
	v_mfma_f32_16x16x32_bf16 v[44:47], v[174:177], v[226:229], v[44:47]
	v_mfma_f32_16x16x32_bf16 v[32:35], v[160:163], v[234:237], v[32:35]
	v_mfma_f32_16x16x32_bf16 v[28:31], v[174:177], v[234:237], v[28:31]
	v_mfma_f32_16x16x32_bf16 v[16:19], v[160:163], v[242:245], v[16:19]
	v_mfma_f32_16x16x32_bf16 v[12:15], v[174:177], v[242:245], v[12:15]
	s_setprio 0
	s_setprio 1
	v_mfma_f32_16x16x32_bf16 v[56:59], v[182:185], v[214:217], v[56:59]
	v_mfma_f32_16x16x32_bf16 v[52:55], v[190:193], v[214:217], v[52:55]
	v_mfma_f32_16x16x32_bf16 v[40:43], v[182:185], v[222:225], v[40:43]
	v_mfma_f32_16x16x32_bf16 v[36:39], v[190:193], v[222:225], v[36:39]
	v_mfma_f32_16x16x32_bf16 v[24:27], v[182:185], v[230:233], v[24:27]
	v_mfma_f32_16x16x32_bf16 v[20:23], v[190:193], v[230:233], v[20:23]
	v_mfma_f32_16x16x32_bf16 v[8:11], v[182:185], v[238:241], v[8:11]
	v_mfma_f32_16x16x32_bf16 v[4:7], v[190:193], v[238:241], v[4:7]
	v_mfma_f32_16x16x32_bf16 v[56:59], v[186:189], v[218:221], v[56:59]
	v_mfma_f32_16x16x32_bf16 v[52:55], v[210:213], v[218:221], v[52:55]
	v_mfma_f32_16x16x32_bf16 v[40:43], v[186:189], v[226:229], v[40:43]
	v_mfma_f32_16x16x32_bf16 v[36:39], v[210:213], v[226:229], v[36:39]
	v_mfma_f32_16x16x32_bf16 v[24:27], v[186:189], v[234:237], v[24:27]
	v_mfma_f32_16x16x32_bf16 v[20:23], v[210:213], v[234:237], v[20:23]
	v_mfma_f32_16x16x32_bf16 v[8:11], v[186:189], v[242:245], v[8:11]
	v_mfma_f32_16x16x32_bf16 v[4:7], v[210:213], v[242:245], v[4:7]
	s_setprio 0
	s_barrier
; #define PG8_STAGE(bufoff, gbase, voff) do { _Pragma("unroll") for (int _i = 0; _i < 2; ++_i) \
;         __builtin_amdgcn_global_load_lds((const unsigned*)((const char*)(gbase) + (voff)[_i]), (PG8_LAS unsigned*)(lds + (bufoff) + ldsw + _i * 8192), 16, 0, 0); } while (0)
; #define PG8_LDA(dst, b, h) do { _Pragma("unroll") for (int m = 0; m < 4; ++m) _Pragma("unroll") for (int k = 0; k < 2; ++k) dst[m][k] = *(const PG8_LAS bf16x8*)(lds + PG8_SA(b, h) + aoff + m * 2048 + k * 1024); } while (0)
; #define PG8_LDB(dst, b, h) do { _Pragma("unroll") for (int n = 0; n < 2; ++n) _Pragma("unroll") for (int k = 0; k < 2; ++k) dst[n][k] = *(const PG8_LAS bf16x8*)(lds + PG8_SB(b, h) + boff + n * 2048 + k * 1024); } while (0)
; #define PG8_MMA(ai, bj, At, Bt) do { __builtin_amdgcn_s_setprio(1); _Pragma("unroll") for (int m = 0; m < 4; ++m) _Pragma("unroll") for (int n = 0; n < 2; ++n) _Pragma("unroll") for (int k = 0; k < 2; ++k) \
;         acc[ai][bj][m][n] = __builtin_amdgcn_mfma_f32_16x16x32_bf16(Bt[n][k], At[m][k], acc[ai][bj][m][n], 0, 0, 0); __builtin_amdgcn_s_setprio(0); } while (0)
; #define PG8_WAIT_V(n) asm volatile("s_waitcnt vmcnt(" #n ")" ::: "memory")
; #define PG8_WAIT_L(n) asm volatile("s_waitcnt lgkmcnt(" #n ")" ::: "memory")
; #define PG8_BAR __builtin_amdgcn_s_barrier()
; #define PG8_SCHED __builtin_amdgcn_sched_barrier(0)
; template <class Epi, class Sched, bool ALIGN_EPI = false, bool SP2 = false>
; __device__ __forceinline__ void gemm_phase(PG8_LAS unsigned char* lds, const Gemm g, const Sched& S, const Epi& E, const int tid_arg) {
;     ...
;             PG8_LDB(B0, 1, 0); PG8_LDB(B1, 1, 1); PG8_SCHED; PG8_LDA(At, 1, 0); PG8_STAGE(PG8_SA(0, 1), a2 + hstep, voffA);
;             PG8_WAIT_V(8); PG8_WAIT_L(0); PG8_BAR; PG8_MMA(0, 0, At, B0); PG8_MMA(0, 1, At, B1); PG8_BAR; PG8_SCHED;
	s_add_i32 s41, 0, 0x18000
	v_add_u32_e32 v2, s41, v167
	s_add_i32 s42, 0, 0x1c000
	ds_read_b128 v[156:159], v2
	ds_read_b128 v[160:163], v2 offset:1024
	ds_read_b128 v[170:173], v2 offset:2048
	ds_read_b128 v[174:177], v2 offset:3072
	v_add_u32_e32 v2, s42, v167
	ds_read_b128 v[182:185], v2
	ds_read_b128 v[186:189], v2 offset:1024
	ds_read_b128 v[190:193], v2 offset:2048
	ds_read_b128 v[210:213], v2 offset:3072
	s_add_u32 s38, s38, 0x40000
	s_addc_u32 s39, s39, 0
	s_mov_b32 m0, s57
	v_lshl_add_u64 v[248:249], s[38:39], 0, v[132:133]
	ds_read_b128 v[214:217], v169 offset:32768
	ds_read_b128 v[218:221], v169 offset:33792
	ds_read_b128 v[222:225], v169 offset:34816
	ds_read_b128 v[226:229], v169 offset:35840
	ds_read_b128 v[230:233], v169 offset:36864
	ds_read_b128 v[234:237], v169 offset:37888
	ds_read_b128 v[238:241], v169 offset:38912
	ds_read_b128 v[242:245], v169 offset:39936
	global_load_lds_dwordx4 v[248:249], off
	v_lshl_add_u64 v[248:249], s[38:39], 0, v[136:137]
	s_mov_b32 m0, s58
	s_nop 0
	global_load_lds_dwordx4 v[248:249], off
	s_waitcnt vmcnt(8)
	s_waitcnt lgkmcnt(0)
	s_barrier
	s_setprio 1
	s_waitcnt lgkmcnt(0)
	v_mfma_f32_16x16x32_bf16 v[128:131], v[156:159], v[214:217], v[128:131]
	v_mfma_f32_16x16x32_bf16 v[124:127], v[170:173], v[214:217], v[124:127]
	v_mfma_f32_16x16x32_bf16 v[112:115], v[156:159], v[222:225], v[112:115]
	v_mfma_f32_16x16x32_bf16 v[108:111], v[170:173], v[222:225], v[108:111]
	v_mfma_f32_16x16x32_bf16 v[96:99], v[156:159], v[230:233], v[96:99]
	v_mfma_f32_16x16x32_bf16 v[92:95], v[170:173], v[230:233], v[92:95]
	v_mfma_f32_16x16x32_bf16 v[80:83], v[156:159], v[238:241], v[80:83]
	v_mfma_f32_16x16x32_bf16 v[76:79], v[170:173], v[238:241], v[76:79]
	v_mfma_f32_16x16x32_bf16 v[128:131], v[160:163], v[218:221], v[128:131]
	v_mfma_f32_16x16x32_bf16 v[124:127], v[174:177], v[218:221], v[124:127]
	v_mfma_f32_16x16x32_bf16 v[112:115], v[160:163], v[226:229], v[112:115]
	v_mfma_f32_16x16x32_bf16 v[108:111], v[174:177], v[226:229], v[108:111]
	v_mfma_f32_16x16x32_bf16 v[96:99], v[160:163], v[234:237], v[96:99]
	v_mfma_f32_16x16x32_bf16 v[92:95], v[174:177], v[234:237], v[92:95]
	v_mfma_f32_16x16x32_bf16 v[80:83], v[160:163], v[242:245], v[80:83]
	v_mfma_f32_16x16x32_bf16 v[76:79], v[174:177], v[242:245], v[76:79]
	s_setprio 0
	s_setprio 1
	v_mfma_f32_16x16x32_bf16 v[120:123], v[182:185], v[214:217], v[120:123]
	v_mfma_f32_16x16x32_bf16 v[116:119], v[190:193], v[214:217], v[116:119]
	v_mfma_f32_16x16x32_bf16 v[104:107], v[182:185], v[222:225], v[104:107]
	v_mfma_f32_16x16x32_bf16 v[100:103], v[190:193], v[222:225], v[100:103]
	v_mfma_f32_16x16x32_bf16 v[88:91], v[182:185], v[230:233], v[88:91]
	v_mfma_f32_16x16x32_bf16 v[84:87], v[190:193], v[230:233], v[84:87]
	v_mfma_f32_16x16x32_bf16 v[72:75], v[182:185], v[238:241], v[72:75]
	v_mfma_f32_16x16x32_bf16 v[68:71], v[190:193], v[238:241], v[68:71]
	v_mfma_f32_16x16x32_bf16 v[120:123], v[186:189], v[218:221], v[120:123]
	v_mfma_f32_16x16x32_bf16 v[116:119], v[210:213], v[218:221], v[116:119]
	v_mfma_f32_16x16x32_bf16 v[104:107], v[186:189], v[226:229], v[104:107]
	v_mfma_f32_16x16x32_bf16 v[100:103], v[210:213], v[226:229], v[100:103]
	v_mfma_f32_16x16x32_bf16 v[88:91], v[186:189], v[234:237], v[88:91]
	v_mfma_f32_16x16x32_bf16 v[84:87], v[210:213], v[234:237], v[84:87]
	v_mfma_f32_16x16x32_bf16 v[72:75], v[186:189], v[242:245], v[72:75]
	v_mfma_f32_16x16x32_bf16 v[68:71], v[210:213], v[242:245], v[68:71]
	s_setprio 0
	s_barrier
; #define PG8_STAGE(bufoff, gbase, voff) do { _Pragma("unroll") for (int _i = 0; _i < 2; ++_i) \
;         __builtin_amdgcn_global_load_lds((const unsigned*)((const char*)(gbase) + (voff)[_i]), (PG8_LAS unsigned*)(lds + (bufoff) + ldsw + _i * 8192), 16, 0, 0); } while (0)
; #define PG8_LDA(dst, b, h) do { _Pragma("unroll") for (int m = 0; m < 4; ++m) _Pragma("unroll") for (int k = 0; k < 2; ++k) dst[m][k] = *(const PG8_LAS bf16x8*)(lds + PG8_SA(b, h) + aoff + m * 2048 + k * 1024); } while (0)
; #define PG8_MMA(ai, bj, At, Bt) do { __builtin_amdgcn_s_setprio(1); _Pragma("unroll") for (int m = 0; m < 4; ++m) _Pragma("unroll") for (int n = 0; n < 2; ++n) _Pragma("unroll") for (int k = 0; k < 2; ++k) \
;         acc[ai][bj][m][n] = __builtin_amdgcn_mfma_f32_16x16x32_bf16(Bt[n][k], At[m][k], acc[ai][bj][m][n], 0, 0, 0); __builtin_amdgcn_s_setprio(0); } while (0)
; #define PG8_WAIT_V(n) asm volatile("s_waitcnt vmcnt(" #n ")" ::: "memory")
; #define PG8_WAIT_L(n) asm volatile("s_waitcnt lgkmcnt(" #n ")" ::: "memory")
; #define PG8_BAR __builtin_amdgcn_s_barrier()
; #define PG8_SCHED __builtin_amdgcn_sched_barrier(0)
; template <class Epi, class Sched, bool ALIGN_EPI = false, bool SP2 = false>
; __device__ __forceinline__ void gemm_phase(PG8_LAS unsigned char* lds, const Gemm g, const Sched& S, const Epi& E, const int tid_arg) {
;     ...
;         for (int t = 0; t < nt; t += 2) {
;             const bool last = (t == nt - 2);
;             const char* a1 = cA + (size_t)(t + 1) * kstep;
;             const char* a2 = last ? nA : cA + (size_t)(t + 2) * kstep; const char* b2 = last ? nB : cB + (size_t)(t + 2) * kstep;
;     ...
;             PG8_LDA(At, 1, 1); PG8_STAGE(PG8_SB(1, 0), b3, voffB); PG8_STAGE(PG8_SB(1, 1), b3 + hstep, voffB); PG8_STAGE(PG8_SA(1, 0), a3, voffA);
;             PG8_WAIT_V(8); PG8_WAIT_L(0); PG8_BAR; PG8_MMA(1, 0, At, B0); PG8_MMA(1, 1, At, B1); PG8_BAR; PG8_SCHED;
	s_add_i32 s38, s41, s54
	v_lshl_add_u64 v[164:165], v[164:165], 0, s[76:77]
	s_mov_b32 m0, s38
	ds_read_b128 v[214:217], v169 offset:49152
	ds_read_b128 v[218:221], v169 offset:50176
	ds_read_b128 v[222:225], v169 offset:51200
	ds_read_b128 v[226:229], v169 offset:52224
	ds_read_b128 v[230:233], v169 offset:53248
	ds_read_b128 v[234:237], v169 offset:54272
	ds_read_b128 v[238:241], v169 offset:55296
	ds_read_b128 v[242:245], v169 offset:56320
	global_load_lds_dwordx4 v[164:165], off
	s_add_i32 m0, s38, 0x2000
	s_add_u32 s36, s36, 0x40080
	v_lshl_add_u64 v[164:165], v[178:179], 0, s[76:77]
	s_addc_u32 s37, s37, 0
	s_add_i32 s38, s42, s54
	global_load_lds_dwordx4 v[164:165], off
	v_lshl_add_u64 v[164:165], s[36:37], 0, v[134:135]
	s_mov_b32 m0, s38
	s_nop 0
	global_load_lds_dwordx4 v[164:165], off
	v_lshl_add_u64 v[164:165], s[36:37], 0, v[138:139]
	s_add_i32 m0, s38, 0x2000
	s_nop 0
	global_load_lds_dwordx4 v[164:165], off
	v_lshl_add_u64 v[164:165], v[194:195], 0, s[76:77]
	s_mov_b32 m0, s61
	s_nop 0
	global_load_lds_dwordx4 v[164:165], off
	v_lshl_add_u64 v[164:165], v[246:247], 0, s[76:77]
	s_mov_b32 m0, s62
	s_nop 0
	global_load_lds_dwordx4 v[164:165], off
	s_waitcnt vmcnt(8)
	s_waitcnt lgkmcnt(0)
	s_barrier
	s_setprio 1
	s_waitcnt lgkmcnt(0)
	v_mfma_f32_16x16x32_bf16 v[64:67], v[156:159], v[214:217], v[64:67]
	v_mfma_f32_16x16x32_bf16 v[60:63], v[170:173], v[214:217], v[60:63]
	v_mfma_f32_16x16x32_bf16 v[48:51], v[156:159], v[222:225], v[48:51]
	v_mfma_f32_16x16x32_bf16 v[44:47], v[170:173], v[222:225], v[44:47]
	v_mfma_f32_16x16x32_bf16 v[32:35], v[156:159], v[230:233], v[32:35]
	v_mfma_f32_16x16x32_bf16 v[28:31], v[170:173], v[230:233], v[28:31]
	v_mfma_f32_16x16x32_bf16 v[16:19], v[156:159], v[238:241], v[16:19]
	v_mfma_f32_16x16x32_bf16 v[12:15], v[170:173], v[238:241], v[12:15]
	v_mfma_f32_16x16x32_bf16 v[64:67], v[160:163], v[218:221], v[64:67]
	v_mfma_f32_16x16x32_bf16 v[60:63], v[174:177], v[218:221], v[60:63]
	v_mfma_f32_16x16x32_bf16 v[48:51], v[160:163], v[226:229], v[48:51]
	v_mfma_f32_16x16x32_bf16 v[44:47], v[174:177], v[226:229], v[44:47]
	v_mfma_f32_16x16x32_bf16 v[32:35], v[160:163], v[234:237], v[32:35]
	v_mfma_f32_16x16x32_bf16 v[28:31], v[174:177], v[234:237], v[28:31]
	v_mfma_f32_16x16x32_bf16 v[16:19], v[160:163], v[242:245], v[16:19]
	v_mfma_f32_16x16x32_bf16 v[12:15], v[174:177], v[242:245], v[12:15]
	s_setprio 0
	s_setprio 1
	v_mfma_f32_16x16x32_bf16 v[56:59], v[182:185], v[214:217], v[56:59]
	v_mfma_f32_16x16x32_bf16 v[52:55], v[190:193], v[214:217], v[52:55]
	v_mfma_f32_16x16x32_bf16 v[40:43], v[182:185], v[222:225], v[40:43]
	v_mfma_f32_16x16x32_bf16 v[36:39], v[190:193], v[222:225], v[36:39]
	v_mfma_f32_16x16x32_bf16 v[24:27], v[182:185], v[230:233], v[24:27]
	v_mfma_f32_16x16x32_bf16 v[20:23], v[190:193], v[230:233], v[20:23]
	v_mfma_f32_16x16x32_bf16 v[8:11], v[182:185], v[238:241], v[8:11]
	v_mfma_f32_16x16x32_bf16 v[4:7], v[190:193], v[238:241], v[4:7]
	v_mfma_f32_16x16x32_bf16 v[56:59], v[186:189], v[218:221], v[56:59]
	v_mfma_f32_16x16x32_bf16 v[52:55], v[210:213], v[218:221], v[52:55]
	v_mfma_f32_16x16x32_bf16 v[40:43], v[186:189], v[226:229], v[40:43]
	v_mfma_f32_16x16x32_bf16 v[36:39], v[210:213], v[226:229], v[36:39]
	v_mfma_f32_16x16x32_bf16 v[24:27], v[186:189], v[234:237], v[24:27]
	v_mfma_f32_16x16x32_bf16 v[20:23], v[210:213], v[234:237], v[20:23]
	v_mfma_f32_16x16x32_bf16 v[8:11], v[186:189], v[242:245], v[8:11]
	v_mfma_f32_16x16x32_bf16 v[4:7], v[210:213], v[242:245], v[4:7]
	s_setprio 0
	s_barrier
	s_add_i32 s40, s40, 2
	s_add_u32 s14, s14, 0x100
	s_addc_u32 s15, s15, 0
	s_add_u32 s27, s27, 0x100
	s_addc_u32 s29, s29, 0
	s_cmp_gt_u32 s40, 13
	s_cbranch_scc0 .LBB0_363
	s_and_b64 vcc, exec, s[22:23]
	s_cbranch_vccz .LBB0_449
	s_barrier
	s_cmp_gt_i32 s10, 23
	s_mov_b64 s[14:15], -1
	s_cbranch_scc1 .LBB0_450

; #define PG8_STAGE(bufoff, gbase, voff) do { _Pragma("unroll") for (int _i = 0; _i < 2; ++_i) \
;         __builtin_amdgcn_global_load_lds((const unsigned*)((const char*)(gbase) + (voff)[_i]), (PG8_LAS unsigned*)(lds + (bufoff) + ldsw + _i * 8192), 16, 0, 0); } while (0)
; #define PG8_LDA(dst, b, h) do { _Pragma("unroll") for (int m = 0; m < 4; ++m) _Pragma("unroll") for (int k = 0; k < 2; ++k) dst[m][k] = *(const PG8_LAS bf16x8*)(lds + PG8_SA(b, h) + aoff + m * 2048 + k * 1024); } while (0)
; #define PG8_LDB(dst, b, h) do { _Pragma("unroll") for (int n = 0; n < 2; ++n) _Pragma("unroll") for (int k = 0; k < 2; ++k) dst[n][k] = *(const PG8_LAS bf16x8*)(lds + PG8_SB(b, h) + boff + n * 2048 + k * 1024); } while (0)
; #define PG8_MMA(ai, bj, At, Bt) do { __builtin_amdgcn_s_setprio(1); _Pragma("unroll") for (int m = 0; m < 4; ++m) _Pragma("unroll") for (int n = 0; n < 2; ++n) _Pragma("unroll") for (int k = 0; k < 2; ++k) \
;         acc[ai][bj][m][n] = __builtin_amdgcn_mfma_f32_16x16x32_bf16(Bt[n][k], At[m][k], acc[ai][bj][m][n], 0, 0, 0); __builtin_amdgcn_s_setprio(0); } while (0)
; #define PG8_BAR __builtin_amdgcn_s_barrier()
; template <class Epi, class Sched, bool ALIGN_EPI = false, bool SP2 = false>
; __device__ __forceinline__ void gemm_phase(PG8_LAS unsigned char* lds, const Gemm g, const Sched& S, const Epi& E, const int tid_arg) {
;     ...
;         for (int t = 0; t < nt; t += 2) {
;             const bool last = (t == nt - 2);
;             const char* a1 = cA + (size_t)(t + 1) * kstep;
;             const char* a2 = last ? nA : cA + (size_t)(t + 2) * kstep; const char* b2 = last ? nB : cB + (size_t)(t + 2) * kstep;
;             const char* a3 = a2 + kstep; const char* b3 = b2 + kstep;
;             if (last && has_next) S.a_ready(nxt);
;             if constexpr (SP2) {
;             PG8_LDB(B0, 0, 0); PG8_LDB(B1, 0, 1); PG8_SCHED; PG8_LDA(At, 0, 0); PG8_STAGE(PG8_SA(1, 1), a1 + hstep, voffA);
;             PG8_WAIT_V(8); PG8_WAIT_L(0); PG8_BAR; PG8_MMA(0, 0, At, B0); PG8_MMA(0, 1, At, B1); PG8_BAR; PG8_SCHED;
;     ...
; #pragma unroll
;         for (int a = 0; a < 2; ++a)
; #pragma unroll
;             for (int b = 0; b < 2; ++b)
; #pragma unroll
;                 for (int m = 0; m < 4; ++m)
; #pragma unroll
;                     for (int n = 0; n < 2; ++n) acc[a][b][m][n] = (f32x4){0.f, 0.f, 0.f, 0.f};
;         cur = nxt; cA = nA; cB = nB; ++ui;
.LBB0_763:
	s_ashr_i32 s27, s26, 31
	s_lshl_b64 s[28:29], s[26:27], 19
	s_add_u32 s28, s3, s28
	s_addc_u32 s29, s6, s29
	s_and_b64 s[30:31], s[10:11], exec
	s_cselect_b32 s27, s29, s5
	s_cselect_b32 s48, s28, s4
	s_ashr_i32 s25, s24, 31
	s_lshl_b64 s[30:31], s[24:25], 19
	s_add_u32 s30, s7, s30
	s_addc_u32 s31, s38, s31
	s_and_b64 s[36:37], s[10:11], exec
	s_cselect_b32 s25, s31, s35
	s_cselect_b32 s49, s30, s34
	s_add_u32 s4, s4, 0x40080
	s_addc_u32 s5, s5, 0
	s_add_u32 s50, s34, 0x100
	v_mov_b32_e32 v4, 0
	s_addc_u32 s51, s35, 0
	s_mov_b32 s52, -2
	v_mov_b32_e32 v5, v4
	v_mov_b32_e32 v6, v4
	v_mov_b32_e32 v7, v4
	v_mov_b32_e32 v8, v4
	v_mov_b32_e32 v9, v4
	v_mov_b32_e32 v10, v4
	v_mov_b32_e32 v11, v4
	v_mov_b32_e32 v20, v4
	v_mov_b32_e32 v21, v4
	v_mov_b32_e32 v22, v4
	v_mov_b32_e32 v23, v4
	v_mov_b32_e32 v24, v4
	v_mov_b32_e32 v25, v4
	v_mov_b32_e32 v26, v4
	v_mov_b32_e32 v27, v4
	v_mov_b32_e32 v36, v4
	v_mov_b32_e32 v37, v4
	v_mov_b32_e32 v38, v4
	v_mov_b32_e32 v39, v4
	v_mov_b32_e32 v40, v4
	v_mov_b32_e32 v41, v4
	v_mov_b32_e32 v42, v4
	v_mov_b32_e32 v43, v4
	v_mov_b32_e32 v52, v4
	v_mov_b32_e32 v53, v4
	v_mov_b32_e32 v54, v4
	v_mov_b32_e32 v55, v4
	v_mov_b32_e32 v56, v4
	v_mov_b32_e32 v57, v4
	v_mov_b32_e32 v58, v4
	v_mov_b32_e32 v59, v4
	v_mov_b32_e32 v12, v4
	v_mov_b32_e32 v13, v4
	v_mov_b32_e32 v14, v4
	v_mov_b32_e32 v15, v4
	v_mov_b32_e32 v16, v4
	v_mov_b32_e32 v17, v4
	v_mov_b32_e32 v18, v4
	v_mov_b32_e32 v19, v4
	v_mov_b32_e32 v28, v4
	v_mov_b32_e32 v29, v4
	v_mov_b32_e32 v30, v4
	v_mov_b32_e32 v31, v4
	v_mov_b32_e32 v32, v4
	v_mov_b32_e32 v33, v4
	v_mov_b32_e32 v34, v4
	v_mov_b32_e32 v35, v4
	v_mov_b32_e32 v44, v4
	v_mov_b32_e32 v45, v4
	v_mov_b32_e32 v46, v4
	v_mov_b32_e32 v47, v4
	v_mov_b32_e32 v48, v4
	v_mov_b32_e32 v49, v4
	v_mov_b32_e32 v50, v4
	v_mov_b32_e32 v51, v4
	v_mov_b32_e32 v60, v4
	v_mov_b32_e32 v61, v4
	v_mov_b32_e32 v62, v4
	v_mov_b32_e32 v63, v4
	v_mov_b32_e32 v64, v4
	v_mov_b32_e32 v65, v4
	v_mov_b32_e32 v66, v4
	v_mov_b32_e32 v67, v4
	v_mov_b32_e32 v68, v4
	v_mov_b32_e32 v69, v4
	v_mov_b32_e32 v70, v4
	v_mov_b32_e32 v71, v4
	v_mov_b32_e32 v72, v4
	v_mov_b32_e32 v73, v4
	v_mov_b32_e32 v74, v4
	v_mov_b32_e32 v75, v4
	v_mov_b32_e32 v84, v4
	v_mov_b32_e32 v85, v4
	v_mov_b32_e32 v86, v4
	v_mov_b32_e32 v87, v4
	v_mov_b32_e32 v88, v4
	v_mov_b32_e32 v89, v4
	v_mov_b32_e32 v90, v4
	v_mov_b32_e32 v91, v4
	v_mov_b32_e32 v100, v4
	v_mov_b32_e32 v101, v4
	v_mov_b32_e32 v102, v4
	v_mov_b32_e32 v103, v4
	v_mov_b32_e32 v104, v4
	v_mov_b32_e32 v105, v4
	v_mov_b32_e32 v106, v4
	v_mov_b32_e32 v107, v4
	v_mov_b32_e32 v116, v4
	v_mov_b32_e32 v117, v4
	v_mov_b32_e32 v118, v4
	v_mov_b32_e32 v119, v4
	s_waitcnt vmcnt(0)
	v_mov_b32_e32 v120, v4
	v_mov_b32_e32 v121, v4
	v_mov_b32_e32 v122, v4
	v_mov_b32_e32 v123, v4
	v_mov_b32_e32 v76, v4
	v_mov_b32_e32 v77, v4
	v_mov_b32_e32 v78, v4
	v_mov_b32_e32 v79, v4
	v_mov_b32_e32 v80, v4
	v_mov_b32_e32 v81, v4
	v_mov_b32_e32 v82, v4
	v_mov_b32_e32 v83, v4
	v_mov_b32_e32 v92, v4
	v_mov_b32_e32 v93, v4
	v_mov_b32_e32 v94, v4
	v_mov_b32_e32 v95, v4
	v_mov_b32_e32 v96, v4
	v_mov_b32_e32 v97, v4
	v_mov_b32_e32 v98, v4
	v_mov_b32_e32 v99, v4
	v_mov_b32_e32 v108, v4
	v_mov_b32_e32 v109, v4
	v_mov_b32_e32 v110, v4
	v_mov_b32_e32 v111, v4
	v_mov_b32_e32 v112, v4
	v_mov_b32_e32 v113, v4
	v_mov_b32_e32 v114, v4
	v_mov_b32_e32 v115, v4
	v_mov_b32_e32 v124, v4
	v_mov_b32_e32 v125, v4
	v_mov_b32_e32 v126, v4
	v_mov_b32_e32 v127, v4
	v_mov_b32_e32 v128, v4
	v_mov_b32_e32 v129, v4
	v_mov_b32_e32 v130, v4
	v_mov_b32_e32 v131, v4
	.p2align 6
	s_nop 0
	s_nop 0
	s_nop 0
	s_nop 0
	s_nop 0
.LBB0_764:
	s_add_u32 s34, s4, 0xfffc0080
	s_addc_u32 s35, s5, -1
	s_add_i32 s53, 0, 0x10000
	s_cmp_eq_u32 s52, 12
	s_cselect_b32 s37, s27, s35
	s_cselect_b32 s36, s48, s34
	s_cselect_b32 s35, s25, s51
	s_cselect_b32 s34, s49, s50
	s_add_i32 s56, 0, 0x14000
	v_add_u32_e32 v164, s53, v153
	v_add_u32_e32 v180, s56, v153
	ds_read_b128 v[148:151], v164
	ds_read_b128 v[156:159], v164 offset:1024
	ds_read_b128 v[160:163], v164 offset:2048
	ds_read_b128 v[164:167], v164 offset:3072
	ds_read_b128 v[168:171], v180
	ds_read_b128 v[172:175], v180 offset:1024
	ds_read_b128 v[176:179], v180 offset:2048
	ds_read_b128 v[182:185], v180 offset:3072
	v_lshl_add_u64 v[194:195], s[4:5], 0, v[138:139]
	s_add_i32 m0, s40, 0xc000
	ds_read_b128 v[186:189], v155
	ds_read_b128 v[190:193], v155 offset:1024
	ds_read_b128 v[210:213], v155 offset:2048
	ds_read_b128 v[214:217], v155 offset:3072
	ds_read_b128 v[218:221], v155 offset:4096
	ds_read_b128 v[222:225], v155 offset:5120
	ds_read_b128 v[226:229], v155 offset:6144
	ds_read_b128 v[230:233], v155 offset:7168
	global_load_lds_dwordx4 v[194:195], off
	v_lshl_add_u64 v[194:195], s[4:5], 0, v[146:147]
	s_add_i32 m0, s40, 0xe000
	s_nop 0
	global_load_lds_dwordx4 v[194:195], off
	s_waitcnt vmcnt(8)
	s_waitcnt lgkmcnt(0)
	s_barrier
; #define PG8_STAGE(bufoff, gbase, voff) do { _Pragma("unroll") for (int _i = 0; _i < 2; ++_i) \
;         __builtin_amdgcn_global_load_lds((const unsigned*)((const char*)(gbase) + (voff)[_i]), (PG8_LAS unsigned*)(lds + (bufoff) + ldsw + _i * 8192), 16, 0, 0); } while (0)
; #define PG8_LDA(dst, b, h) do { _Pragma("unroll") for (int m = 0; m < 4; ++m) _Pragma("unroll") for (int k = 0; k < 2; ++k) dst[m][k] = *(const PG8_LAS bf16x8*)(lds + PG8_SA(b, h) + aoff + m * 2048 + k * 1024); } while (0)
; #define PG8_MMA(ai, bj, At, Bt) do { __builtin_amdgcn_s_setprio(1); _Pragma("unroll") for (int m = 0; m < 4; ++m) _Pragma("unroll") for (int n = 0; n < 2; ++n) _Pragma("unroll") for (int k = 0; k < 2; ++k) \
;         acc[ai][bj][m][n] = __builtin_amdgcn_mfma_f32_16x16x32_bf16(Bt[n][k], At[m][k], acc[ai][bj][m][n], 0, 0, 0); __builtin_amdgcn_s_setprio(0); } while (0)
; #define PG8_WAIT_V(n) asm volatile("s_waitcnt vmcnt(" #n ")" ::: "memory")
; #define PG8_WAIT_L(n) asm volatile("s_waitcnt lgkmcnt(" #n ")" ::: "memory")
; #define PG8_BAR __builtin_amdgcn_s_barrier()
; #define PG8_SCHED __builtin_amdgcn_sched_barrier(0)
; template <class Epi, class Sched, bool ALIGN_EPI = false, bool SP2 = false>
; __device__ __forceinline__ void gemm_phase(PG8_LAS unsigned char* lds, const Gemm g, const Sched& S, const Epi& E, const int tid_arg) {
;     ...
;             PG8_WAIT_V(8); PG8_WAIT_L(0); PG8_BAR; PG8_MMA(0, 0, At, B0); PG8_MMA(0, 1, At, B1); PG8_BAR; PG8_SCHED;
;             PG8_LDA(At, 0, 1); PG8_STAGE(PG8_SB(0, 0), b2, voffB); PG8_STAGE(PG8_SB(0, 1), b2 + hstep, voffB); PG8_STAGE(PG8_SA(0, 0), a2, voffA);
;             PG8_WAIT_V(8); PG8_WAIT_L(0); PG8_BAR; PG8_MMA(1, 0, At, B0); PG8_MMA(1, 1, At, B1); PG8_BAR; PG8_SCHED;
	s_setprio 1
	s_waitcnt lgkmcnt(0)
	v_mfma_f32_16x16x32_bf16 v[128:131], v[148:151], v[186:189], v[128:131]
	v_mfma_f32_16x16x32_bf16 v[124:127], v[160:163], v[186:189], v[124:127]
	v_mfma_f32_16x16x32_bf16 v[112:115], v[148:151], v[210:213], v[112:115]
	v_mfma_f32_16x16x32_bf16 v[108:111], v[160:163], v[210:213], v[108:111]
	v_mfma_f32_16x16x32_bf16 v[96:99], v[148:151], v[218:221], v[96:99]
	v_mfma_f32_16x16x32_bf16 v[92:95], v[160:163], v[218:221], v[92:95]
	v_mfma_f32_16x16x32_bf16 v[80:83], v[148:151], v[226:229], v[80:83]
	v_mfma_f32_16x16x32_bf16 v[76:79], v[160:163], v[226:229], v[76:79]
	v_mfma_f32_16x16x32_bf16 v[128:131], v[156:159], v[190:193], v[128:131]
	v_mfma_f32_16x16x32_bf16 v[124:127], v[164:167], v[190:193], v[124:127]
	v_mfma_f32_16x16x32_bf16 v[112:115], v[156:159], v[214:217], v[112:115]
	v_mfma_f32_16x16x32_bf16 v[108:111], v[164:167], v[214:217], v[108:111]
	v_mfma_f32_16x16x32_bf16 v[96:99], v[156:159], v[222:225], v[96:99]
	v_mfma_f32_16x16x32_bf16 v[92:95], v[164:167], v[222:225], v[92:95]
	v_mfma_f32_16x16x32_bf16 v[80:83], v[156:159], v[230:233], v[80:83]
	v_mfma_f32_16x16x32_bf16 v[76:79], v[164:167], v[230:233], v[76:79]
	s_setprio 0
	s_setprio 1
	v_mfma_f32_16x16x32_bf16 v[120:123], v[168:171], v[186:189], v[120:123]
	v_mfma_f32_16x16x32_bf16 v[116:119], v[176:179], v[186:189], v[116:119]
	v_mfma_f32_16x16x32_bf16 v[104:107], v[168:171], v[210:213], v[104:107]
	v_mfma_f32_16x16x32_bf16 v[100:103], v[176:179], v[210:213], v[100:103]
	v_mfma_f32_16x16x32_bf16 v[88:91], v[168:171], v[218:221], v[88:91]
	v_mfma_f32_16x16x32_bf16 v[84:87], v[176:179], v[218:221], v[84:87]
	v_mfma_f32_16x16x32_bf16 v[72:75], v[168:171], v[226:229], v[72:75]
	v_mfma_f32_16x16x32_bf16 v[68:71], v[176:179], v[226:229], v[68:71]
	v_mfma_f32_16x16x32_bf16 v[120:123], v[172:175], v[190:193], v[120:123]
	v_mfma_f32_16x16x32_bf16 v[116:119], v[182:185], v[190:193], v[116:119]
	v_mfma_f32_16x16x32_bf16 v[104:107], v[172:175], v[214:217], v[104:107]
	v_mfma_f32_16x16x32_bf16 v[100:103], v[182:185], v[214:217], v[100:103]
	v_mfma_f32_16x16x32_bf16 v[88:91], v[172:175], v[222:225], v[88:91]
	v_mfma_f32_16x16x32_bf16 v[84:87], v[182:185], v[222:225], v[84:87]
	v_mfma_f32_16x16x32_bf16 v[72:75], v[172:175], v[230:233], v[72:75]
	v_mfma_f32_16x16x32_bf16 v[68:71], v[182:185], v[230:233], v[68:71]
	s_setprio 0
	s_barrier
	s_add_i32 s53, s53, s39
	v_lshl_add_u64 v[194:195], s[34:35], 0, v[2:3]
	s_mov_b32 m0, s53
	ds_read_b128 v[186:189], v155 offset:16384
	ds_read_b128 v[190:193], v155 offset:17408
	ds_read_b128 v[210:213], v155 offset:18432
	ds_read_b128 v[214:217], v155 offset:19456
	ds_read_b128 v[218:221], v155 offset:20480
	ds_read_b128 v[222:225], v155 offset:21504
	ds_read_b128 v[226:229], v155 offset:22528
	ds_read_b128 v[230:233], v155 offset:23552
	global_load_lds_dwordx4 v[194:195], off
	s_add_i32 m0, s53, 0x2000
	s_add_u32 s54, s34, 0x40000
	v_lshl_add_u64 v[234:235], s[34:35], 0, v[132:133]
	s_addc_u32 s55, s35, 0
	s_add_i32 s53, s56, s39
	global_load_lds_dwordx4 v[234:235], off
	v_lshl_add_u64 v[236:237], s[54:55], 0, v[2:3]
	s_mov_b32 m0, s53
	v_lshl_add_u64 v[238:239], s[36:37], 0, v[134:135]
	global_load_lds_dwordx4 v[236:237], off
	v_lshl_add_u64 v[236:237], s[54:55], 0, v[132:133]
	s_add_i32 m0, s53, 0x2000
	s_nop 0
	global_load_lds_dwordx4 v[236:237], off
	v_lshl_add_u64 v[236:237], s[36:37], 0, v[136:137]
	s_mov_b32 m0, s40
	s_nop 0
	global_load_lds_dwordx4 v[236:237], off
	s_mov_b32 m0, s41
	s_nop 0
	global_load_lds_dwordx4 v[238:239], off
	s_waitcnt vmcnt(8)
	s_waitcnt lgkmcnt(0)
	s_barrier
	s_setprio 1
	s_waitcnt lgkmcnt(0)
	v_mfma_f32_16x16x32_bf16 v[64:67], v[148:151], v[186:189], v[64:67]
	v_mfma_f32_16x16x32_bf16 v[60:63], v[160:163], v[186:189], v[60:63]
	v_mfma_f32_16x16x32_bf16 v[48:51], v[148:151], v[210:213], v[48:51]
	v_mfma_f32_16x16x32_bf16 v[44:47], v[160:163], v[210:213], v[44:47]
	v_mfma_f32_16x16x32_bf16 v[32:35], v[148:151], v[218:221], v[32:35]
	v_mfma_f32_16x16x32_bf16 v[28:31], v[160:163], v[218:221], v[28:31]
	v_mfma_f32_16x16x32_bf16 v[16:19], v[148:151], v[226:229], v[16:19]
	v_mfma_f32_16x16x32_bf16 v[12:15], v[160:163], v[226:229], v[12:15]
	v_mfma_f32_16x16x32_bf16 v[64:67], v[156:159], v[190:193], v[64:67]
	v_mfma_f32_16x16x32_bf16 v[60:63], v[164:167], v[190:193], v[60:63]
	v_mfma_f32_16x16x32_bf16 v[48:51], v[156:159], v[214:217], v[48:51]
	v_mfma_f32_16x16x32_bf16 v[44:47], v[164:167], v[214:217], v[44:47]
	v_mfma_f32_16x16x32_bf16 v[32:35], v[156:159], v[222:225], v[32:35]
	v_mfma_f32_16x16x32_bf16 v[28:31], v[164:167], v[222:225], v[28:31]
	v_mfma_f32_16x16x32_bf16 v[16:19], v[156:159], v[230:233], v[16:19]
	v_mfma_f32_16x16x32_bf16 v[12:15], v[164:167], v[230:233], v[12:15]
	s_setprio 0
	s_setprio 1
	v_mfma_f32_16x16x32_bf16 v[56:59], v[168:171], v[186:189], v[56:59]
	v_mfma_f32_16x16x32_bf16 v[52:55], v[176:179], v[186:189], v[52:55]
	v_mfma_f32_16x16x32_bf16 v[40:43], v[168:171], v[210:213], v[40:43]
	v_mfma_f32_16x16x32_bf16 v[36:39], v[176:179], v[210:213], v[36:39]
	v_mfma_f32_16x16x32_bf16 v[24:27], v[168:171], v[218:221], v[24:27]
	v_mfma_f32_16x16x32_bf16 v[20:23], v[176:179], v[218:221], v[20:23]
	v_mfma_f32_16x16x32_bf16 v[8:11], v[168:171], v[226:229], v[8:11]
	v_mfma_f32_16x16x32_bf16 v[4:7], v[176:179], v[226:229], v[4:7]
	v_mfma_f32_16x16x32_bf16 v[56:59], v[172:175], v[190:193], v[56:59]
	v_mfma_f32_16x16x32_bf16 v[52:55], v[182:185], v[190:193], v[52:55]
	v_mfma_f32_16x16x32_bf16 v[40:43], v[172:175], v[214:217], v[40:43]
	v_mfma_f32_16x16x32_bf16 v[36:39], v[182:185], v[214:217], v[36:39]
	v_mfma_f32_16x16x32_bf16 v[24:27], v[172:175], v[222:225], v[24:27]
	v_mfma_f32_16x16x32_bf16 v[20:23], v[182:185], v[222:225], v[20:23]
	v_mfma_f32_16x16x32_bf16 v[8:11], v[172:175], v[230:233], v[8:11]
	v_mfma_f32_16x16x32_bf16 v[4:7], v[182:185], v[230:233], v[4:7]
	s_setprio 0
	s_barrier
; #define PG8_STAGE(bufoff, gbase, voff) do { _Pragma("unroll") for (int _i = 0; _i < 2; ++_i) \
;         __builtin_amdgcn_global_load_lds((const unsigned*)((const char*)(gbase) + (voff)[_i]), (PG8_LAS unsigned*)(lds + (bufoff) + ldsw + _i * 8192), 16, 0, 0); } while (0)
; #define PG8_LDA(dst, b, h) do { _Pragma("unroll") for (int m = 0; m < 4; ++m) _Pragma("unroll") for (int k = 0; k < 2; ++k) dst[m][k] = *(const PG8_LAS bf16x8*)(lds + PG8_SA(b, h) + aoff + m * 2048 + k * 1024); } while (0)
; #define PG8_LDB(dst, b, h) do { _Pragma("unroll") for (int n = 0; n < 2; ++n) _Pragma("unroll") for (int k = 0; k < 2; ++k) dst[n][k] = *(const PG8_LAS bf16x8*)(lds + PG8_SB(b, h) + boff + n * 2048 + k * 1024); } while (0)
; #define PG8_MMA(ai, bj, At, Bt) do { __builtin_amdgcn_s_setprio(1); _Pragma("unroll") for (int m = 0; m < 4; ++m) _Pragma("unroll") for (int n = 0; n < 2; ++n) _Pragma("unroll") for (int k = 0; k < 2; ++k) \
;         acc[ai][bj][m][n] = __builtin_amdgcn_mfma_f32_16x16x32_bf16(Bt[n][k], At[m][k], acc[ai][bj][m][n], 0, 0, 0); __builtin_amdgcn_s_setprio(0); } while (0)
; #define PG8_WAIT_V(n) asm volatile("s_waitcnt vmcnt(" #n ")" ::: "memory")
; #define PG8_WAIT_L(n) asm volatile("s_waitcnt lgkmcnt(" #n ")" ::: "memory")
; #define PG8_BAR __builtin_amdgcn_s_barrier()
; #define PG8_SCHED __builtin_amdgcn_sched_barrier(0)
; template <class Epi, class Sched, bool ALIGN_EPI = false, bool SP2 = false>
; __device__ __forceinline__ void gemm_phase(PG8_LAS unsigned char* lds, const Gemm g, const Sched& S, const Epi& E, const int tid_arg) {
;     ...
;             PG8_LDB(B0, 1, 0); PG8_LDB(B1, 1, 1); PG8_SCHED; PG8_LDA(At, 1, 0); PG8_STAGE(PG8_SA(0, 1), a2 + hstep, voffA);
;             PG8_WAIT_V(8); PG8_WAIT_L(0); PG8_BAR; PG8_MMA(0, 0, At, B0); PG8_MMA(0, 1, At, B1); PG8_BAR; PG8_SCHED;
	s_add_i32 s53, 0, 0x18000
	s_add_i32 s54, 0, 0x1c000
	v_add_u32_e32 v164, s53, v153
	v_add_u32_e32 v180, s54, v153
	ds_read_b128 v[148:151], v164
	ds_read_b128 v[156:159], v164 offset:1024
	ds_read_b128 v[160:163], v164 offset:2048
	ds_read_b128 v[164:167], v164 offset:3072
	ds_read_b128 v[168:171], v180
	ds_read_b128 v[172:175], v180 offset:1024
	ds_read_b128 v[176:179], v180 offset:2048
	ds_read_b128 v[182:185], v180 offset:3072
	s_add_u32 s36, s36, 0x40000
	s_addc_u32 s37, s37, 0
	s_mov_b32 m0, s42
	v_lshl_add_u64 v[240:241], s[36:37], 0, v[136:137]
	ds_read_b128 v[186:189], v155 offset:32768
	ds_read_b128 v[190:193], v155 offset:33792
	ds_read_b128 v[210:213], v155 offset:34816
	ds_read_b128 v[214:217], v155 offset:35840
	ds_read_b128 v[218:221], v155 offset:36864
	ds_read_b128 v[222:225], v155 offset:37888
	ds_read_b128 v[226:229], v155 offset:38912
	ds_read_b128 v[230:233], v155 offset:39936
	global_load_lds_dwordx4 v[240:241], off
	v_lshl_add_u64 v[240:241], s[36:37], 0, v[134:135]
	s_mov_b32 m0, s43
	s_nop 0
	global_load_lds_dwordx4 v[240:241], off
	s_waitcnt vmcnt(8)
	s_waitcnt lgkmcnt(0)
	s_barrier
	s_setprio 1
	s_waitcnt lgkmcnt(0)
	v_mfma_f32_16x16x32_bf16 v[128:131], v[148:151], v[186:189], v[128:131]
	v_mfma_f32_16x16x32_bf16 v[124:127], v[160:163], v[186:189], v[124:127]
	v_mfma_f32_16x16x32_bf16 v[112:115], v[148:151], v[210:213], v[112:115]
	v_mfma_f32_16x16x32_bf16 v[108:111], v[160:163], v[210:213], v[108:111]
	v_mfma_f32_16x16x32_bf16 v[96:99], v[148:151], v[218:221], v[96:99]
	v_mfma_f32_16x16x32_bf16 v[92:95], v[160:163], v[218:221], v[92:95]
	v_mfma_f32_16x16x32_bf16 v[80:83], v[148:151], v[226:229], v[80:83]
	v_mfma_f32_16x16x32_bf16 v[76:79], v[160:163], v[226:229], v[76:79]
	v_mfma_f32_16x16x32_bf16 v[128:131], v[156:159], v[190:193], v[128:131]
	v_mfma_f32_16x16x32_bf16 v[124:127], v[164:167], v[190:193], v[124:127]
	v_mfma_f32_16x16x32_bf16 v[112:115], v[156:159], v[214:217], v[112:115]
	v_mfma_f32_16x16x32_bf16 v[108:111], v[164:167], v[214:217], v[108:111]
	v_mfma_f32_16x16x32_bf16 v[96:99], v[156:159], v[222:225], v[96:99]
	v_mfma_f32_16x16x32_bf16 v[92:95], v[164:167], v[222:225], v[92:95]
	v_mfma_f32_16x16x32_bf16 v[80:83], v[156:159], v[230:233], v[80:83]
	v_mfma_f32_16x16x32_bf16 v[76:79], v[164:167], v[230:233], v[76:79]
	s_setprio 0
	s_setprio 1
	v_mfma_f32_16x16x32_bf16 v[120:123], v[168:171], v[186:189], v[120:123]
	v_mfma_f32_16x16x32_bf16 v[116:119], v[176:179], v[186:189], v[116:119]
	v_mfma_f32_16x16x32_bf16 v[104:107], v[168:171], v[210:213], v[104:107]
	v_mfma_f32_16x16x32_bf16 v[100:103], v[176:179], v[210:213], v[100:103]
	v_mfma_f32_16x16x32_bf16 v[88:91], v[168:171], v[218:221], v[88:91]
	v_mfma_f32_16x16x32_bf16 v[84:87], v[176:179], v[218:221], v[84:87]
	v_mfma_f32_16x16x32_bf16 v[72:75], v[168:171], v[226:229], v[72:75]
	v_mfma_f32_16x16x32_bf16 v[68:71], v[176:179], v[226:229], v[68:71]
	v_mfma_f32_16x16x32_bf16 v[120:123], v[172:175], v[190:193], v[120:123]
	v_mfma_f32_16x16x32_bf16 v[116:119], v[182:185], v[190:193], v[116:119]
	v_mfma_f32_16x16x32_bf16 v[104:107], v[172:175], v[214:217], v[104:107]
	v_mfma_f32_16x16x32_bf16 v[100:103], v[182:185], v[214:217], v[100:103]
	v_mfma_f32_16x16x32_bf16 v[88:91], v[172:175], v[222:225], v[88:91]
	v_mfma_f32_16x16x32_bf16 v[84:87], v[182:185], v[222:225], v[84:87]
	v_mfma_f32_16x16x32_bf16 v[72:75], v[172:175], v[230:233], v[72:75]
	v_mfma_f32_16x16x32_bf16 v[68:71], v[182:185], v[230:233], v[68:71]
	s_setprio 0
	s_barrier
; #define PG8_STAGE(bufoff, gbase, voff) do { _Pragma("unroll") for (int _i = 0; _i < 2; ++_i) \
;         __builtin_amdgcn_global_load_lds((const unsigned*)((const char*)(gbase) + (voff)[_i]), (PG8_LAS unsigned*)(lds + (bufoff) + ldsw + _i * 8192), 16, 0, 0); } while (0)
; #define PG8_LDA(dst, b, h) do { _Pragma("unroll") for (int m = 0; m < 4; ++m) _Pragma("unroll") for (int k = 0; k < 2; ++k) dst[m][k] = *(const PG8_LAS bf16x8*)(lds + PG8_SA(b, h) + aoff + m * 2048 + k * 1024); } while (0)
; #define PG8_MMA(ai, bj, At, Bt) do { __builtin_amdgcn_s_setprio(1); _Pragma("unroll") for (int m = 0; m < 4; ++m) _Pragma("unroll") for (int n = 0; n < 2; ++n) _Pragma("unroll") for (int k = 0; k < 2; ++k) \
;         acc[ai][bj][m][n] = __builtin_amdgcn_mfma_f32_16x16x32_bf16(Bt[n][k], At[m][k], acc[ai][bj][m][n], 0, 0, 0); __builtin_amdgcn_s_setprio(0); } while (0)
; #define PG8_WAIT_V(n) asm volatile("s_waitcnt vmcnt(" #n ")" ::: "memory")
; #define PG8_WAIT_L(n) asm volatile("s_waitcnt lgkmcnt(" #n ")" ::: "memory")
; #define PG8_BAR __builtin_amdgcn_s_barrier()
; #define PG8_SCHED __builtin_amdgcn_sched_barrier(0)
; template <class Epi, class Sched, bool ALIGN_EPI = false, bool SP2 = false>
; __device__ __forceinline__ void gemm_phase(PG8_LAS unsigned char* lds, const Gemm g, const Sched& S, const Epi& E, const int tid_arg) {
;     ...
;         for (int t = 0; t < nt; t += 2) {
;             const bool last = (t == nt - 2);
;             const char* a1 = cA + (size_t)(t + 1) * kstep;
;             const char* a2 = last ? nA : cA + (size_t)(t + 2) * kstep; const char* b2 = last ? nB : cB + (size_t)(t + 2) * kstep;
;     ...
;             PG8_LDA(At, 1, 1); PG8_STAGE(PG8_SB(1, 0), b3, voffB); PG8_STAGE(PG8_SB(1, 1), b3 + hstep, voffB); PG8_STAGE(PG8_SA(1, 0), a3, voffA);
;             PG8_WAIT_V(8); PG8_WAIT_L(0); PG8_BAR; PG8_MMA(1, 0, At, B0); PG8_MMA(1, 1, At, B1); PG8_BAR; PG8_SCHED;
	s_add_i32 s36, s53, s39
	v_lshl_add_u64 v[194:195], v[194:195], 0, s[76:77]
	s_mov_b32 m0, s36
	ds_read_b128 v[186:189], v155 offset:49152
	ds_read_b128 v[190:193], v155 offset:50176
	ds_read_b128 v[210:213], v155 offset:51200
	ds_read_b128 v[214:217], v155 offset:52224
	ds_read_b128 v[218:221], v155 offset:53248
	ds_read_b128 v[222:225], v155 offset:54272
	ds_read_b128 v[226:229], v155 offset:55296
	ds_read_b128 v[230:233], v155 offset:56320
	global_load_lds_dwordx4 v[194:195], off
	s_add_i32 m0, s36, 0x2000
	s_add_u32 s34, s34, 0x40080
	v_lshl_add_u64 v[194:195], v[234:235], 0, s[76:77]
	s_addc_u32 s35, s35, 0
	s_add_i32 s36, s54, s39
	global_load_lds_dwordx4 v[194:195], off
	v_lshl_add_u64 v[194:195], s[34:35], 0, v[2:3]
	s_mov_b32 m0, s36
	s_nop 0
	global_load_lds_dwordx4 v[194:195], off
	v_lshl_add_u64 v[194:195], s[34:35], 0, v[132:133]
	s_add_i32 m0, s36, 0x2000
	s_nop 0
	global_load_lds_dwordx4 v[194:195], off
	v_lshl_add_u64 v[194:195], v[236:237], 0, s[76:77]
	s_mov_b32 m0, s44
	s_nop 0
	global_load_lds_dwordx4 v[194:195], off
	v_lshl_add_u64 v[194:195], v[238:239], 0, s[76:77]
	s_mov_b32 m0, s45
	s_nop 0
	global_load_lds_dwordx4 v[194:195], off
	s_waitcnt vmcnt(8)
	s_waitcnt lgkmcnt(0)
	s_barrier
	s_setprio 1
	s_waitcnt lgkmcnt(0)
	v_mfma_f32_16x16x32_bf16 v[64:67], v[148:151], v[186:189], v[64:67]
	v_mfma_f32_16x16x32_bf16 v[60:63], v[160:163], v[186:189], v[60:63]
	v_mfma_f32_16x16x32_bf16 v[48:51], v[148:151], v[210:213], v[48:51]
	v_mfma_f32_16x16x32_bf16 v[44:47], v[160:163], v[210:213], v[44:47]
	v_mfma_f32_16x16x32_bf16 v[32:35], v[148:151], v[218:221], v[32:35]
	v_mfma_f32_16x16x32_bf16 v[28:31], v[160:163], v[218:221], v[28:31]
	v_mfma_f32_16x16x32_bf16 v[16:19], v[148:151], v[226:229], v[16:19]
	v_mfma_f32_16x16x32_bf16 v[12:15], v[160:163], v[226:229], v[12:15]
	v_mfma_f32_16x16x32_bf16 v[64:67], v[156:159], v[190:193], v[64:67]
	v_mfma_f32_16x16x32_bf16 v[60:63], v[164:167], v[190:193], v[60:63]
	v_mfma_f32_16x16x32_bf16 v[48:51], v[156:159], v[214:217], v[48:51]
	v_mfma_f32_16x16x32_bf16 v[44:47], v[164:167], v[214:217], v[44:47]
	v_mfma_f32_16x16x32_bf16 v[32:35], v[156:159], v[222:225], v[32:35]
	v_mfma_f32_16x16x32_bf16 v[28:31], v[164:167], v[222:225], v[28:31]
	v_mfma_f32_16x16x32_bf16 v[16:19], v[156:159], v[230:233], v[16:19]
	v_mfma_f32_16x16x32_bf16 v[12:15], v[164:167], v[230:233], v[12:15]
	s_setprio 0
	s_setprio 1
	v_mfma_f32_16x16x32_bf16 v[56:59], v[168:171], v[186:189], v[56:59]
	v_mfma_f32_16x16x32_bf16 v[52:55], v[176:179], v[186:189], v[52:55]
	v_mfma_f32_16x16x32_bf16 v[40:43], v[168:171], v[210:213], v[40:43]
	v_mfma_f32_16x16x32_bf16 v[36:39], v[176:179], v[210:213], v[36:39]
	v_mfma_f32_16x16x32_bf16 v[24:27], v[168:171], v[218:221], v[24:27]
	v_mfma_f32_16x16x32_bf16 v[20:23], v[176:179], v[218:221], v[20:23]
	v_mfma_f32_16x16x32_bf16 v[8:11], v[168:171], v[226:229], v[8:11]
	v_mfma_f32_16x16x32_bf16 v[4:7], v[176:179], v[226:229], v[4:7]
	v_mfma_f32_16x16x32_bf16 v[56:59], v[172:175], v[190:193], v[56:59]
	v_mfma_f32_16x16x32_bf16 v[52:55], v[182:185], v[190:193], v[52:55]
	v_mfma_f32_16x16x32_bf16 v[40:43], v[172:175], v[214:217], v[40:43]
	v_mfma_f32_16x16x32_bf16 v[36:39], v[182:185], v[214:217], v[36:39]
	v_mfma_f32_16x16x32_bf16 v[24:27], v[172:175], v[222:225], v[24:27]
	v_mfma_f32_16x16x32_bf16 v[20:23], v[182:185], v[222:225], v[20:23]
	v_mfma_f32_16x16x32_bf16 v[8:11], v[172:175], v[230:233], v[8:11]
	v_mfma_f32_16x16x32_bf16 v[4:7], v[182:185], v[230:233], v[4:7]
	s_setprio 0
	s_barrier
	s_add_i32 s52, s52, 2
	s_add_u32 s4, s4, 0x100
	s_addc_u32 s5, s5, 0
	s_add_u32 s50, s50, 0x100
	s_addc_u32 s51, s51, 0
	s_cmp_gt_u32 s52, 13
	s_cbranch_scc0 .LBB0_764
	s_and_b64 vcc, exec, s[22:23]
	s_cbranch_vccz .LBB0_767
	s_barrier

; template <class Epi, class Sched, bool ALIGN_EPI = false, bool SP2 = false>
; __device__ __forceinline__ void gemm_phase(PG8_LAS unsigned char* lds, const Gemm g, const Sched& S, const Epi& E, const int tid_arg) {
;     ...
;         const bool has_next = S.next(ui + 1, nxt);
;         const char* nA = has_next ? (const char*)g.A + (size_t)nxt.pm * tstep : cA; const char* nB = has_next ? (const char*)g.Bt + (size_t)nxt.pn * tstep : cB;
;     ...
; #pragma unroll
;         for (int a = 0; a < 2; ++a)
; #pragma unroll
;             for (int b = 0; b < 2; ++b)
; #pragma unroll
;                 for (int m = 0; m < 4; ++m)
; #pragma unroll
;                     for (int n = 0; n < 2; ++n) acc[a][b][m][n] = (f32x4){0.f, 0.f, 0.f, 0.f};
;         cur = nxt; cA = nA; cB = nB; ++ui;
.LBB0_789:
	s_ashr_i32 s27, s26, 31
	s_lshl_b64 s[28:29], s[26:27], 19
	s_add_u32 s28, s40, s28
	s_addc_u32 s29, s41, s29
	s_and_b64 s[30:31], s[10:11], exec
	s_cselect_b32 s27, s29, s35
	s_cselect_b32 s52, s28, s34
	s_ashr_i32 s25, s24, 31
	s_lshl_b64 s[30:31], s[24:25], 19
	s_add_u32 s30, s42, s30
	s_addc_u32 s31, s43, s31
	s_and_b64 s[38:39], s[10:11], exec
	s_cselect_b32 s25, s31, s37
	s_cselect_b32 s53, s30, s36
	s_add_u32 s34, s34, 0x40080
	s_addc_u32 s35, s35, 0
	s_add_u32 s54, s36, 0x100
	v_mov_b32_e32 v4, 0
	s_addc_u32 s55, s37, 0
	s_mov_b32 s56, -2
	v_mov_b32_e32 v5, v4
	v_mov_b32_e32 v6, v4
	v_mov_b32_e32 v7, v4
	v_mov_b32_e32 v8, v4
	v_mov_b32_e32 v9, v4
	v_mov_b32_e32 v10, v4
	v_mov_b32_e32 v11, v4
	v_mov_b32_e32 v20, v4
	v_mov_b32_e32 v21, v4
	v_mov_b32_e32 v22, v4
	v_mov_b32_e32 v23, v4
	v_mov_b32_e32 v24, v4
	v_mov_b32_e32 v25, v4
	v_mov_b32_e32 v26, v4
	v_mov_b32_e32 v27, v4
	v_mov_b32_e32 v36, v4
	v_mov_b32_e32 v37, v4
	v_mov_b32_e32 v38, v4
	v_mov_b32_e32 v39, v4
	v_mov_b32_e32 v40, v4
	v_mov_b32_e32 v41, v4
	v_mov_b32_e32 v42, v4
	v_mov_b32_e32 v43, v4
	v_mov_b32_e32 v52, v4
	v_mov_b32_e32 v53, v4
	v_mov_b32_e32 v54, v4
	v_mov_b32_e32 v55, v4
	v_mov_b32_e32 v56, v4
	v_mov_b32_e32 v57, v4
	v_mov_b32_e32 v58, v4
	v_mov_b32_e32 v59, v4
	v_mov_b32_e32 v12, v4
	v_mov_b32_e32 v13, v4
	v_mov_b32_e32 v14, v4
	v_mov_b32_e32 v15, v4
	v_mov_b32_e32 v16, v4
	v_mov_b32_e32 v17, v4
	v_mov_b32_e32 v18, v4
	v_mov_b32_e32 v19, v4
	v_mov_b32_e32 v28, v4
	v_mov_b32_e32 v29, v4
	v_mov_b32_e32 v30, v4
	v_mov_b32_e32 v31, v4
	v_mov_b32_e32 v32, v4
	v_mov_b32_e32 v33, v4
	v_mov_b32_e32 v34, v4
	v_mov_b32_e32 v35, v4
	v_mov_b32_e32 v44, v4
	v_mov_b32_e32 v45, v4
	v_mov_b32_e32 v46, v4
	v_mov_b32_e32 v47, v4
	v_mov_b32_e32 v48, v4
	v_mov_b32_e32 v49, v4
	v_mov_b32_e32 v50, v4
	v_mov_b32_e32 v51, v4
	v_mov_b32_e32 v60, v4
	v_mov_b32_e32 v61, v4
	v_mov_b32_e32 v62, v4
	v_mov_b32_e32 v63, v4
	v_mov_b32_e32 v64, v4
	v_mov_b32_e32 v65, v4
	v_mov_b32_e32 v66, v4
	v_mov_b32_e32 v67, v4
	v_mov_b32_e32 v68, v4
	v_mov_b32_e32 v69, v4
	v_mov_b32_e32 v70, v4
	v_mov_b32_e32 v71, v4
	v_mov_b32_e32 v72, v4
	v_mov_b32_e32 v73, v4
	v_mov_b32_e32 v74, v4
	v_mov_b32_e32 v75, v4
	v_mov_b32_e32 v84, v4
	v_mov_b32_e32 v85, v4
	v_mov_b32_e32 v86, v4
	v_mov_b32_e32 v87, v4
	v_mov_b32_e32 v88, v4
	v_mov_b32_e32 v89, v4
	v_mov_b32_e32 v90, v4
	v_mov_b32_e32 v91, v4
	v_mov_b32_e32 v100, v4
	v_mov_b32_e32 v101, v4
	v_mov_b32_e32 v102, v4
	v_mov_b32_e32 v103, v4
	v_mov_b32_e32 v104, v4
	v_mov_b32_e32 v105, v4
	v_mov_b32_e32 v106, v4
	v_mov_b32_e32 v107, v4
	v_mov_b32_e32 v116, v4
	v_mov_b32_e32 v117, v4
	v_mov_b32_e32 v118, v4
	v_mov_b32_e32 v119, v4
	s_waitcnt vmcnt(0)
	v_mov_b32_e32 v120, v4
	v_mov_b32_e32 v121, v4
	v_mov_b32_e32 v122, v4
	v_mov_b32_e32 v123, v4
	v_mov_b32_e32 v76, v4
	v_mov_b32_e32 v77, v4
	v_mov_b32_e32 v78, v4
	v_mov_b32_e32 v79, v4
	v_mov_b32_e32 v80, v4
	v_mov_b32_e32 v81, v4
	v_mov_b32_e32 v82, v4
	v_mov_b32_e32 v83, v4
	v_mov_b32_e32 v92, v4
	v_mov_b32_e32 v93, v4
	v_mov_b32_e32 v94, v4
	v_mov_b32_e32 v95, v4
	v_mov_b32_e32 v96, v4
	v_mov_b32_e32 v97, v4
	v_mov_b32_e32 v98, v4
	v_mov_b32_e32 v99, v4
	v_mov_b32_e32 v108, v4
	v_mov_b32_e32 v109, v4
	v_mov_b32_e32 v110, v4
	v_mov_b32_e32 v111, v4
	v_mov_b32_e32 v112, v4
	v_mov_b32_e32 v113, v4
	v_mov_b32_e32 v114, v4
	v_mov_b32_e32 v115, v4
	v_mov_b32_e32 v124, v4
	v_mov_b32_e32 v125, v4
	v_mov_b32_e32 v126, v4
	v_mov_b32_e32 v127, v4
	v_mov_b32_e32 v128, v4
	v_mov_b32_e32 v129, v4
	v_mov_b32_e32 v130, v4
	v_mov_b32_e32 v131, v4
	.p2align 6
	s_nop 0
	s_nop 0
	s_nop 0
	s_nop 0
	s_nop 0

; #define PG8_STAGE(bufoff, gbase, voff) do { _Pragma("unroll") for (int _i = 0; _i < 2; ++_i) \
;         __builtin_amdgcn_global_load_lds((const unsigned*)((const char*)(gbase) + (voff)[_i]), (PG8_LAS unsigned*)(lds + (bufoff) + ldsw + _i * 8192), 16, 0, 0); } while (0)
; #define PG8_LDA(dst, b, h) do { _Pragma("unroll") for (int m = 0; m < 4; ++m) _Pragma("unroll") for (int k = 0; k < 2; ++k) dst[m][k] = *(const PG8_LAS bf16x8*)(lds + PG8_SA(b, h) + aoff + m * 2048 + k * 1024); } while (0)
; #define PG8_LDB(dst, b, h) do { _Pragma("unroll") for (int n = 0; n < 2; ++n) _Pragma("unroll") for (int k = 0; k < 2; ++k) dst[n][k] = *(const PG8_LAS bf16x8*)(lds + PG8_SB(b, h) + boff + n * 2048 + k * 1024); } while (0)
; #define PG8_MMA(ai, bj, At, Bt) do { __builtin_amdgcn_s_setprio(1); _Pragma("unroll") for (int m = 0; m < 4; ++m) _Pragma("unroll") for (int n = 0; n < 2; ++n) _Pragma("unroll") for (int k = 0; k < 2; ++k) \
;         acc[ai][bj][m][n] = __builtin_amdgcn_mfma_f32_16x16x32_bf16(Bt[n][k], At[m][k], acc[ai][bj][m][n], 0, 0, 0); __builtin_amdgcn_s_setprio(0); } while (0)
; #define PG8_BAR __builtin_amdgcn_s_barrier()
; template <class Epi, class Sched, bool ALIGN_EPI = false, bool SP2 = false>
; __device__ __forceinline__ void gemm_phase(PG8_LAS unsigned char* lds, const Gemm g, const Sched& S, const Epi& E, const int tid_arg) {
;     ...
;         for (int t = 0; t < nt; t += 2) {
;             const bool last = (t == nt - 2);
;             const char* a1 = cA + (size_t)(t + 1) * kstep;
;             const char* a2 = last ? nA : cA + (size_t)(t + 2) * kstep; const char* b2 = last ? nB : cB + (size_t)(t + 2) * kstep;
;             const char* a3 = a2 + kstep; const char* b3 = b2 + kstep;
;             if (last && has_next) S.a_ready(nxt);
;             if constexpr (SP2) {
;             PG8_LDB(B0, 0, 0); PG8_LDB(B1, 0, 1); PG8_SCHED; PG8_LDA(At, 0, 0); PG8_STAGE(PG8_SA(1, 1), a1 + hstep, voffA);
;             PG8_WAIT_V(8); PG8_WAIT_L(0); PG8_BAR; PG8_MMA(0, 0, At, B0); PG8_MMA(0, 1, At, B1); PG8_BAR; PG8_SCHED;
;     ...
; #pragma unroll
;         for (int a = 0; a < 2; ++a)
; #pragma unroll
;             for (int b = 0; b < 2; ++b)
; #pragma unroll
;                 for (int m = 0; m < 4; ++m)
; #pragma unroll
;                     for (int n = 0; n < 2; ++n) acc[a][b][m][n] = (f32x4){0.f, 0.f, 0.f, 0.f};
;         cur = nxt; cA = nA; cB = nB; ++ui;
.LBB0_867:
	s_ashr_i32 s35, s34, 31
	s_lshl_b64 s[36:37], s[34:35], 19
	s_add_u32 s36, s2, s36
	s_addc_u32 s37, s47, s37
	s_and_b64 s[38:39], s[14:15], exec
	s_cselect_b32 s7, s37, s17
	s_cselect_b32 s35, s36, s16
	s_ashr_i32 s31, s30, 31
	s_lshl_b64 s[38:39], s[30:31], 19
	s_add_u32 s38, s48, s38
	s_addc_u32 s39, s49, s39
	s_and_b64 s[44:45], s[14:15], exec
	s_cselect_b32 s31, s39, s43
	s_cselect_b32 s41, s38, s42
	s_add_u32 s16, s16, 0x40080
	s_addc_u32 s17, s17, 0
	s_add_u32 s59, s42, 0x100
	v_mov_b32_e32 v4, 0
	s_addc_u32 s60, s43, 0
	s_mov_b32 s61, -2
	s_waitcnt lgkmcnt(0)
	v_mov_b32_e32 v5, v4
	v_mov_b32_e32 v6, v4
	v_mov_b32_e32 v7, v4
	v_mov_b32_e32 v8, v4
	v_mov_b32_e32 v9, v4
	v_mov_b32_e32 v10, v4
	v_mov_b32_e32 v11, v4
	v_mov_b32_e32 v20, v4
	v_mov_b32_e32 v21, v4
	v_mov_b32_e32 v22, v4
	v_mov_b32_e32 v23, v4
	v_mov_b32_e32 v24, v4
	v_mov_b32_e32 v25, v4
	v_mov_b32_e32 v26, v4
	v_mov_b32_e32 v27, v4
	v_mov_b32_e32 v36, v4
	v_mov_b32_e32 v37, v4
	v_mov_b32_e32 v38, v4
	v_mov_b32_e32 v39, v4
	v_mov_b32_e32 v40, v4
	v_mov_b32_e32 v41, v4
	v_mov_b32_e32 v42, v4
	v_mov_b32_e32 v43, v4
	v_mov_b32_e32 v52, v4
	v_mov_b32_e32 v53, v4
	v_mov_b32_e32 v54, v4
	v_mov_b32_e32 v55, v4
	v_mov_b32_e32 v56, v4
	v_mov_b32_e32 v57, v4
	v_mov_b32_e32 v58, v4
	v_mov_b32_e32 v59, v4
	v_mov_b32_e32 v12, v4
	v_mov_b32_e32 v13, v4
	v_mov_b32_e32 v14, v4
	v_mov_b32_e32 v15, v4
	v_mov_b32_e32 v16, v4
	v_mov_b32_e32 v17, v4
	v_mov_b32_e32 v18, v4
	v_mov_b32_e32 v19, v4
	v_mov_b32_e32 v28, v4
	v_mov_b32_e32 v29, v4
	v_mov_b32_e32 v30, v4
	v_mov_b32_e32 v31, v4
	v_mov_b32_e32 v32, v4
	v_mov_b32_e32 v33, v4
	v_mov_b32_e32 v34, v4
	v_mov_b32_e32 v35, v4
	v_mov_b32_e32 v44, v4
	v_mov_b32_e32 v45, v4
	v_mov_b32_e32 v46, v4
	v_mov_b32_e32 v47, v4
	v_mov_b32_e32 v48, v4
	v_mov_b32_e32 v49, v4
	v_mov_b32_e32 v50, v4
	v_mov_b32_e32 v51, v4
	v_mov_b32_e32 v60, v4
	v_mov_b32_e32 v61, v4
	v_mov_b32_e32 v62, v4
	v_mov_b32_e32 v63, v4
	v_mov_b32_e32 v64, v4
	v_mov_b32_e32 v65, v4
	v_mov_b32_e32 v66, v4
	v_mov_b32_e32 v67, v4
	v_mov_b32_e32 v68, v4
	v_mov_b32_e32 v69, v4
	v_mov_b32_e32 v70, v4
	v_mov_b32_e32 v71, v4
	v_mov_b32_e32 v72, v4
	v_mov_b32_e32 v73, v4
	v_mov_b32_e32 v74, v4
	v_mov_b32_e32 v75, v4
	v_mov_b32_e32 v84, v4
	v_mov_b32_e32 v85, v4
	v_mov_b32_e32 v86, v4
	v_mov_b32_e32 v87, v4
	v_mov_b32_e32 v88, v4
	v_mov_b32_e32 v89, v4
	v_mov_b32_e32 v90, v4
	v_mov_b32_e32 v91, v4
	v_mov_b32_e32 v100, v4
	v_mov_b32_e32 v101, v4
	v_mov_b32_e32 v102, v4
	v_mov_b32_e32 v103, v4
	v_mov_b32_e32 v104, v4
	v_mov_b32_e32 v105, v4
	v_mov_b32_e32 v106, v4
	v_mov_b32_e32 v107, v4
	v_mov_b32_e32 v116, v4
	v_mov_b32_e32 v117, v4
	v_mov_b32_e32 v118, v4
	v_mov_b32_e32 v119, v4
	s_waitcnt vmcnt(0)
	v_mov_b32_e32 v120, v4
	v_mov_b32_e32 v121, v4
	v_mov_b32_e32 v122, v4
	v_mov_b32_e32 v123, v4
	v_mov_b32_e32 v76, v4
	v_mov_b32_e32 v77, v4
	v_mov_b32_e32 v78, v4
	v_mov_b32_e32 v79, v4
	v_mov_b32_e32 v80, v4
	v_mov_b32_e32 v81, v4
	v_mov_b32_e32 v82, v4
	v_mov_b32_e32 v83, v4
	v_mov_b32_e32 v92, v4
	v_mov_b32_e32 v93, v4
	v_mov_b32_e32 v94, v4
	v_mov_b32_e32 v95, v4
	v_mov_b32_e32 v96, v4
	v_mov_b32_e32 v97, v4
	v_mov_b32_e32 v98, v4
	v_mov_b32_e32 v99, v4
	v_mov_b32_e32 v108, v4
	v_mov_b32_e32 v109, v4
	v_mov_b32_e32 v110, v4
	v_mov_b32_e32 v111, v4
	v_mov_b32_e32 v112, v4
	v_mov_b32_e32 v113, v4
	v_mov_b32_e32 v114, v4
	v_mov_b32_e32 v115, v4
	v_mov_b32_e32 v124, v4
	v_mov_b32_e32 v125, v4
	v_mov_b32_e32 v126, v4
	v_mov_b32_e32 v127, v4
	v_mov_b32_e32 v128, v4
	v_mov_b32_e32 v129, v4
	v_mov_b32_e32 v130, v4
	v_mov_b32_e32 v131, v4
	.p2align 6
	s_nop 0
	s_nop 0
	s_nop 0
	s_nop 0
	s_nop 0
.LBB0_868:
	s_add_u32 s42, s16, 0xfffc0080
	s_addc_u32 s43, s17, -1
	s_add_i32 s62, 0, 0x10000
	s_cmp_eq_u32 s61, 12
	s_cselect_b32 s45, s7, s43
	s_cselect_b32 s44, s35, s42
	s_cselect_b32 s43, s31, s60
	s_cselect_b32 s42, s41, s59
	s_add_i32 s64, 0, 0x14000
	v_add_u32_e32 v160, s62, v169
	v_add_u32_e32 v179, s64, v169
	ds_read_b128 v[132:135], v160
	ds_read_b128 v[136:139], v160 offset:1024
	ds_read_b128 v[156:159], v160 offset:2048
	ds_read_b128 v[160:163], v160 offset:3072
	ds_read_b128 v[164:167], v179
	ds_read_b128 v[182:185], v179 offset:1024
	ds_read_b128 v[186:189], v179 offset:2048
	ds_read_b128 v[190:193], v179 offset:3072
	v_lshl_add_u64 v[194:195], s[16:17], 0, v[152:153]
	s_add_i32 m0, s51, 0xc000
	ds_read_b128 v[210:213], v178
	ds_read_b128 v[214:217], v178 offset:1024
	ds_read_b128 v[218:221], v178 offset:2048
	ds_read_b128 v[222:225], v178 offset:3072
	ds_read_b128 v[226:229], v178 offset:4096
	ds_read_b128 v[230:233], v178 offset:5120
	ds_read_b128 v[234:237], v178 offset:6144
	ds_read_b128 v[238:241], v178 offset:7168
	global_load_lds_dwordx4 v[194:195], off
	v_lshl_add_u64 v[194:195], s[16:17], 0, v[154:155]
	s_add_i32 m0, s51, 0xe000
	s_nop 0
	global_load_lds_dwordx4 v[194:195], off
	s_waitcnt vmcnt(8)
	s_waitcnt lgkmcnt(0)
	s_barrier
; #define PG8_STAGE(bufoff, gbase, voff) do { _Pragma("unroll") for (int _i = 0; _i < 2; ++_i) \
;         __builtin_amdgcn_global_load_lds((const unsigned*)((const char*)(gbase) + (voff)[_i]), (PG8_LAS unsigned*)(lds + (bufoff) + ldsw + _i * 8192), 16, 0, 0); } while (0)
; #define PG8_LDA(dst, b, h) do { _Pragma("unroll") for (int m = 0; m < 4; ++m) _Pragma("unroll") for (int k = 0; k < 2; ++k) dst[m][k] = *(const PG8_LAS bf16x8*)(lds + PG8_SA(b, h) + aoff + m * 2048 + k * 1024); } while (0)
; #define PG8_LDB(dst, b, h) do { _Pragma("unroll") for (int n = 0; n < 2; ++n) _Pragma("unroll") for (int k = 0; k < 2; ++k) dst[n][k] = *(const PG8_LAS bf16x8*)(lds + PG8_SB(b, h) + boff + n * 2048 + k * 1024); } while (0)
; #define PG8_MMA(ai, bj, At, Bt) do { __builtin_amdgcn_s_setprio(1); _Pragma("unroll") for (int m = 0; m < 4; ++m) _Pragma("unroll") for (int n = 0; n < 2; ++n) _Pragma("unroll") for (int k = 0; k < 2; ++k) \
;         acc[ai][bj][m][n] = __builtin_amdgcn_mfma_f32_16x16x32_bf16(Bt[n][k], At[m][k], acc[ai][bj][m][n], 0, 0, 0); __builtin_amdgcn_s_setprio(0); } while (0)
; #define PG8_WAIT_V(n) asm volatile("s_waitcnt vmcnt(" #n ")" ::: "memory")
; #define PG8_WAIT_L(n) asm volatile("s_waitcnt lgkmcnt(" #n ")" ::: "memory")
; #define PG8_BAR __builtin_amdgcn_s_barrier()
; #define PG8_SCHED __builtin_amdgcn_sched_barrier(0)
; template <class Epi, class Sched, bool ALIGN_EPI = false, bool SP2 = false>
; __device__ __forceinline__ void gemm_phase(PG8_LAS unsigned char* lds, const Gemm g, const Sched& S, const Epi& E, const int tid_arg) {
;     ...
;             PG8_LDB(B0, 0, 0); PG8_LDB(B1, 0, 1); PG8_SCHED; PG8_LDA(At, 0, 0); PG8_STAGE(PG8_SA(1, 1), a1 + hstep, voffA);
;             PG8_WAIT_V(8); PG8_WAIT_L(0); PG8_BAR; PG8_MMA(0, 0, At, B0); PG8_MMA(0, 1, At, B1); PG8_BAR; PG8_SCHED;
;             PG8_LDA(At, 0, 1); PG8_STAGE(PG8_SB(0, 0), b2, voffB); PG8_STAGE(PG8_SB(0, 1), b2 + hstep, voffB); PG8_STAGE(PG8_SA(0, 0), a2, voffA);
;             PG8_WAIT_V(8); PG8_WAIT_L(0); PG8_BAR; PG8_MMA(1, 0, At, B0); PG8_MMA(1, 1, At, B1); PG8_BAR; PG8_SCHED;
	s_setprio 1
	s_waitcnt lgkmcnt(0)
	v_mfma_f32_16x16x32_bf16 v[128:131], v[132:135], v[210:213], v[128:131]
	v_mfma_f32_16x16x32_bf16 v[124:127], v[156:159], v[210:213], v[124:127]
	v_mfma_f32_16x16x32_bf16 v[112:115], v[132:135], v[218:221], v[112:115]
	v_mfma_f32_16x16x32_bf16 v[108:111], v[156:159], v[218:221], v[108:111]
	v_mfma_f32_16x16x32_bf16 v[96:99], v[132:135], v[226:229], v[96:99]
	v_mfma_f32_16x16x32_bf16 v[92:95], v[156:159], v[226:229], v[92:95]
	v_mfma_f32_16x16x32_bf16 v[80:83], v[132:135], v[234:237], v[80:83]
	v_mfma_f32_16x16x32_bf16 v[76:79], v[156:159], v[234:237], v[76:79]
	v_mfma_f32_16x16x32_bf16 v[128:131], v[136:139], v[214:217], v[128:131]
	v_mfma_f32_16x16x32_bf16 v[124:127], v[160:163], v[214:217], v[124:127]
	v_mfma_f32_16x16x32_bf16 v[112:115], v[136:139], v[222:225], v[112:115]
	v_mfma_f32_16x16x32_bf16 v[108:111], v[160:163], v[222:225], v[108:111]
	v_mfma_f32_16x16x32_bf16 v[96:99], v[136:139], v[230:233], v[96:99]
	v_mfma_f32_16x16x32_bf16 v[92:95], v[160:163], v[230:233], v[92:95]
	v_mfma_f32_16x16x32_bf16 v[80:83], v[136:139], v[238:241], v[80:83]
	v_mfma_f32_16x16x32_bf16 v[76:79], v[160:163], v[238:241], v[76:79]
	s_setprio 0
	s_setprio 1
	v_mfma_f32_16x16x32_bf16 v[120:123], v[164:167], v[210:213], v[120:123]
	v_mfma_f32_16x16x32_bf16 v[116:119], v[186:189], v[210:213], v[116:119]
	v_mfma_f32_16x16x32_bf16 v[104:107], v[164:167], v[218:221], v[104:107]
	v_mfma_f32_16x16x32_bf16 v[100:103], v[186:189], v[218:221], v[100:103]
	v_mfma_f32_16x16x32_bf16 v[88:91], v[164:167], v[226:229], v[88:91]
	v_mfma_f32_16x16x32_bf16 v[84:87], v[186:189], v[226:229], v[84:87]
	v_mfma_f32_16x16x32_bf16 v[72:75], v[164:167], v[234:237], v[72:75]
	v_mfma_f32_16x16x32_bf16 v[68:71], v[186:189], v[234:237], v[68:71]
	v_mfma_f32_16x16x32_bf16 v[120:123], v[182:185], v[214:217], v[120:123]
	v_mfma_f32_16x16x32_bf16 v[116:119], v[190:193], v[214:217], v[116:119]
	v_mfma_f32_16x16x32_bf16 v[104:107], v[182:185], v[222:225], v[104:107]
	v_mfma_f32_16x16x32_bf16 v[100:103], v[190:193], v[222:225], v[100:103]
	v_mfma_f32_16x16x32_bf16 v[88:91], v[182:185], v[230:233], v[88:91]
	v_mfma_f32_16x16x32_bf16 v[84:87], v[190:193], v[230:233], v[84:87]
	v_mfma_f32_16x16x32_bf16 v[72:75], v[182:185], v[238:241], v[72:75]
	v_mfma_f32_16x16x32_bf16 v[68:71], v[190:193], v[238:241], v[68:71]
	s_setprio 0
	s_barrier
	s_add_i32 s62, s62, s50
	v_lshl_add_u64 v[194:195], s[42:43], 0, v[2:3]
	s_mov_b32 m0, s62
	ds_read_b128 v[210:213], v178 offset:16384
	ds_read_b128 v[214:217], v178 offset:17408
	ds_read_b128 v[218:221], v178 offset:18432
	ds_read_b128 v[222:225], v178 offset:19456
	ds_read_b128 v[226:229], v178 offset:20480
	ds_read_b128 v[230:233], v178 offset:21504
	ds_read_b128 v[234:237], v178 offset:22528
	ds_read_b128 v[238:241], v178 offset:23552
	global_load_lds_dwordx4 v[194:195], off
	s_add_i32 m0, s62, 0x2000
	s_add_u32 s62, s42, 0x40000
	v_lshl_add_u64 v[242:243], s[42:43], 0, v[146:147]
	s_addc_u32 s63, s43, 0
	s_add_i32 s64, s64, s50
	global_load_lds_dwordx4 v[242:243], off
	v_lshl_add_u64 v[244:245], s[62:63], 0, v[2:3]
	s_mov_b32 m0, s64
	v_lshl_add_u64 v[246:247], s[44:45], 0, v[148:149]
	global_load_lds_dwordx4 v[244:245], off
	v_lshl_add_u64 v[244:245], s[62:63], 0, v[146:147]
	s_add_i32 m0, s64, 0x2000
	s_nop 0
	global_load_lds_dwordx4 v[244:245], off
	v_lshl_add_u64 v[244:245], s[44:45], 0, v[150:151]
	s_mov_b32 m0, s51
	s_nop 0
	global_load_lds_dwordx4 v[244:245], off
	s_mov_b32 m0, s52
	s_nop 0
	global_load_lds_dwordx4 v[246:247], off
	s_waitcnt vmcnt(8)
	s_waitcnt lgkmcnt(0)
	s_barrier
	s_setprio 1
	s_waitcnt lgkmcnt(0)
	v_mfma_f32_16x16x32_bf16 v[64:67], v[132:135], v[210:213], v[64:67]
	v_mfma_f32_16x16x32_bf16 v[60:63], v[156:159], v[210:213], v[60:63]
	v_mfma_f32_16x16x32_bf16 v[48:51], v[132:135], v[218:221], v[48:51]
	v_mfma_f32_16x16x32_bf16 v[44:47], v[156:159], v[218:221], v[44:47]
	v_mfma_f32_16x16x32_bf16 v[32:35], v[132:135], v[226:229], v[32:35]
	v_mfma_f32_16x16x32_bf16 v[28:31], v[156:159], v[226:229], v[28:31]
	v_mfma_f32_16x16x32_bf16 v[16:19], v[132:135], v[234:237], v[16:19]
	v_mfma_f32_16x16x32_bf16 v[12:15], v[156:159], v[234:237], v[12:15]
	v_mfma_f32_16x16x32_bf16 v[64:67], v[136:139], v[214:217], v[64:67]
	v_mfma_f32_16x16x32_bf16 v[60:63], v[160:163], v[214:217], v[60:63]
	v_mfma_f32_16x16x32_bf16 v[48:51], v[136:139], v[222:225], v[48:51]
	v_mfma_f32_16x16x32_bf16 v[44:47], v[160:163], v[222:225], v[44:47]
	v_mfma_f32_16x16x32_bf16 v[32:35], v[136:139], v[230:233], v[32:35]
	v_mfma_f32_16x16x32_bf16 v[28:31], v[160:163], v[230:233], v[28:31]
	v_mfma_f32_16x16x32_bf16 v[16:19], v[136:139], v[238:241], v[16:19]
	v_mfma_f32_16x16x32_bf16 v[12:15], v[160:163], v[238:241], v[12:15]
	s_setprio 0
	s_setprio 1
	v_mfma_f32_16x16x32_bf16 v[56:59], v[164:167], v[210:213], v[56:59]
	v_mfma_f32_16x16x32_bf16 v[52:55], v[186:189], v[210:213], v[52:55]
	v_mfma_f32_16x16x32_bf16 v[40:43], v[164:167], v[218:221], v[40:43]
	v_mfma_f32_16x16x32_bf16 v[36:39], v[186:189], v[218:221], v[36:39]
	v_mfma_f32_16x16x32_bf16 v[24:27], v[164:167], v[226:229], v[24:27]
	v_mfma_f32_16x16x32_bf16 v[20:23], v[186:189], v[226:229], v[20:23]
	v_mfma_f32_16x16x32_bf16 v[8:11], v[164:167], v[234:237], v[8:11]
	v_mfma_f32_16x16x32_bf16 v[4:7], v[186:189], v[234:237], v[4:7]
	v_mfma_f32_16x16x32_bf16 v[56:59], v[182:185], v[214:217], v[56:59]
	v_mfma_f32_16x16x32_bf16 v[52:55], v[190:193], v[214:217], v[52:55]
	v_mfma_f32_16x16x32_bf16 v[40:43], v[182:185], v[222:225], v[40:43]
	v_mfma_f32_16x16x32_bf16 v[36:39], v[190:193], v[222:225], v[36:39]
	v_mfma_f32_16x16x32_bf16 v[24:27], v[182:185], v[230:233], v[24:27]
	v_mfma_f32_16x16x32_bf16 v[20:23], v[190:193], v[230:233], v[20:23]
	v_mfma_f32_16x16x32_bf16 v[8:11], v[182:185], v[238:241], v[8:11]
	v_mfma_f32_16x16x32_bf16 v[4:7], v[190:193], v[238:241], v[4:7]
	s_setprio 0
	s_barrier
; #define PG8_STAGE(bufoff, gbase, voff) do { _Pragma("unroll") for (int _i = 0; _i < 2; ++_i) \
;         __builtin_amdgcn_global_load_lds((const unsigned*)((const char*)(gbase) + (voff)[_i]), (PG8_LAS unsigned*)(lds + (bufoff) + ldsw + _i * 8192), 16, 0, 0); } while (0)
; #define PG8_LDA(dst, b, h) do { _Pragma("unroll") for (int m = 0; m < 4; ++m) _Pragma("unroll") for (int k = 0; k < 2; ++k) dst[m][k] = *(const PG8_LAS bf16x8*)(lds + PG8_SA(b, h) + aoff + m * 2048 + k * 1024); } while (0)
; #define PG8_LDB(dst, b, h) do { _Pragma("unroll") for (int n = 0; n < 2; ++n) _Pragma("unroll") for (int k = 0; k < 2; ++k) dst[n][k] = *(const PG8_LAS bf16x8*)(lds + PG8_SB(b, h) + boff + n * 2048 + k * 1024); } while (0)
; #define PG8_MMA(ai, bj, At, Bt) do { __builtin_amdgcn_s_setprio(1); _Pragma("unroll") for (int m = 0; m < 4; ++m) _Pragma("unroll") for (int n = 0; n < 2; ++n) _Pragma("unroll") for (int k = 0; k < 2; ++k) \
;         acc[ai][bj][m][n] = __builtin_amdgcn_mfma_f32_16x16x32_bf16(Bt[n][k], At[m][k], acc[ai][bj][m][n], 0, 0, 0); __builtin_amdgcn_s_setprio(0); } while (0)
; #define PG8_WAIT_V(n) asm volatile("s_waitcnt vmcnt(" #n ")" ::: "memory")
; #define PG8_WAIT_L(n) asm volatile("s_waitcnt lgkmcnt(" #n ")" ::: "memory")
; #define PG8_BAR __builtin_amdgcn_s_barrier()
; #define PG8_SCHED __builtin_amdgcn_sched_barrier(0)
; template <class Epi, class Sched, bool ALIGN_EPI = false, bool SP2 = false>
; __device__ __forceinline__ void gemm_phase(PG8_LAS unsigned char* lds, const Gemm g, const Sched& S, const Epi& E, const int tid_arg) {
;     ...
;             PG8_LDB(B0, 1, 0); PG8_LDB(B1, 1, 1); PG8_SCHED; PG8_LDA(At, 1, 0); PG8_STAGE(PG8_SA(0, 1), a2 + hstep, voffA);
;             PG8_WAIT_V(8); PG8_WAIT_L(0); PG8_BAR; PG8_MMA(0, 0, At, B0); PG8_MMA(0, 1, At, B1); PG8_BAR; PG8_SCHED;
	s_add_i32 s62, 0, 0x18000
	s_add_i32 s63, 0, 0x1c000
	v_add_u32_e32 v160, s62, v169
	v_add_u32_e32 v179, s63, v169
	ds_read_b128 v[132:135], v160
	ds_read_b128 v[136:139], v160 offset:1024
	ds_read_b128 v[156:159], v160 offset:2048
	ds_read_b128 v[160:163], v160 offset:3072
	ds_read_b128 v[164:167], v179
	ds_read_b128 v[182:185], v179 offset:1024
	ds_read_b128 v[186:189], v179 offset:2048
	ds_read_b128 v[190:193], v179 offset:3072
	s_add_u32 s44, s44, 0x40000
	s_addc_u32 s45, s45, 0
	s_mov_b32 m0, s53
	v_lshl_add_u64 v[248:249], s[44:45], 0, v[150:151]
	ds_read_b128 v[210:213], v178 offset:32768
	ds_read_b128 v[214:217], v178 offset:33792
	ds_read_b128 v[218:221], v178 offset:34816
	ds_read_b128 v[222:225], v178 offset:35840
	ds_read_b128 v[226:229], v178 offset:36864
	ds_read_b128 v[230:233], v178 offset:37888
	ds_read_b128 v[234:237], v178 offset:38912
	ds_read_b128 v[238:241], v178 offset:39936
	global_load_lds_dwordx4 v[248:249], off
	v_lshl_add_u64 v[248:249], s[44:45], 0, v[148:149]
	s_mov_b32 m0, s54
	s_nop 0
	global_load_lds_dwordx4 v[248:249], off
	s_waitcnt vmcnt(8)
	s_waitcnt lgkmcnt(0)
	s_barrier
	s_setprio 1
	s_waitcnt lgkmcnt(0)
	v_mfma_f32_16x16x32_bf16 v[128:131], v[132:135], v[210:213], v[128:131]
	v_mfma_f32_16x16x32_bf16 v[124:127], v[156:159], v[210:213], v[124:127]
	v_mfma_f32_16x16x32_bf16 v[112:115], v[132:135], v[218:221], v[112:115]
	v_mfma_f32_16x16x32_bf16 v[108:111], v[156:159], v[218:221], v[108:111]
	v_mfma_f32_16x16x32_bf16 v[96:99], v[132:135], v[226:229], v[96:99]
	v_mfma_f32_16x16x32_bf16 v[92:95], v[156:159], v[226:229], v[92:95]
	v_mfma_f32_16x16x32_bf16 v[80:83], v[132:135], v[234:237], v[80:83]
	v_mfma_f32_16x16x32_bf16 v[76:79], v[156:159], v[234:237], v[76:79]
	v_mfma_f32_16x16x32_bf16 v[128:131], v[136:139], v[214:217], v[128:131]
	v_mfma_f32_16x16x32_bf16 v[124:127], v[160:163], v[214:217], v[124:127]
	v_mfma_f32_16x16x32_bf16 v[112:115], v[136:139], v[222:225], v[112:115]
	v_mfma_f32_16x16x32_bf16 v[108:111], v[160:163], v[222:225], v[108:111]
	v_mfma_f32_16x16x32_bf16 v[96:99], v[136:139], v[230:233], v[96:99]
	v_mfma_f32_16x16x32_bf16 v[92:95], v[160:163], v[230:233], v[92:95]
	v_mfma_f32_16x16x32_bf16 v[80:83], v[136:139], v[238:241], v[80:83]
	v_mfma_f32_16x16x32_bf16 v[76:79], v[160:163], v[238:241], v[76:79]
	s_setprio 0
	s_setprio 1
	v_mfma_f32_16x16x32_bf16 v[120:123], v[164:167], v[210:213], v[120:123]
	v_mfma_f32_16x16x32_bf16 v[116:119], v[186:189], v[210:213], v[116:119]
	v_mfma_f32_16x16x32_bf16 v[104:107], v[164:167], v[218:221], v[104:107]
	v_mfma_f32_16x16x32_bf16 v[100:103], v[186:189], v[218:221], v[100:103]
	v_mfma_f32_16x16x32_bf16 v[88:91], v[164:167], v[226:229], v[88:91]
	v_mfma_f32_16x16x32_bf16 v[84:87], v[186:189], v[226:229], v[84:87]
	v_mfma_f32_16x16x32_bf16 v[72:75], v[164:167], v[234:237], v[72:75]
	v_mfma_f32_16x16x32_bf16 v[68:71], v[186:189], v[234:237], v[68:71]
	v_mfma_f32_16x16x32_bf16 v[120:123], v[182:185], v[214:217], v[120:123]
	v_mfma_f32_16x16x32_bf16 v[116:119], v[190:193], v[214:217], v[116:119]
	v_mfma_f32_16x16x32_bf16 v[104:107], v[182:185], v[222:225], v[104:107]
	v_mfma_f32_16x16x32_bf16 v[100:103], v[190:193], v[222:225], v[100:103]
	v_mfma_f32_16x16x32_bf16 v[88:91], v[182:185], v[230:233], v[88:91]
	v_mfma_f32_16x16x32_bf16 v[84:87], v[190:193], v[230:233], v[84:87]
	v_mfma_f32_16x16x32_bf16 v[72:75], v[182:185], v[238:241], v[72:75]
	v_mfma_f32_16x16x32_bf16 v[68:71], v[190:193], v[238:241], v[68:71]
	s_setprio 0
	s_barrier
; #define PG8_STAGE(bufoff, gbase, voff) do { _Pragma("unroll") for (int _i = 0; _i < 2; ++_i) \
;         __builtin_amdgcn_global_load_lds((const unsigned*)((const char*)(gbase) + (voff)[_i]), (PG8_LAS unsigned*)(lds + (bufoff) + ldsw + _i * 8192), 16, 0, 0); } while (0)
; #define PG8_LDA(dst, b, h) do { _Pragma("unroll") for (int m = 0; m < 4; ++m) _Pragma("unroll") for (int k = 0; k < 2; ++k) dst[m][k] = *(const PG8_LAS bf16x8*)(lds + PG8_SA(b, h) + aoff + m * 2048 + k * 1024); } while (0)
; #define PG8_MMA(ai, bj, At, Bt) do { __builtin_amdgcn_s_setprio(1); _Pragma("unroll") for (int m = 0; m < 4; ++m) _Pragma("unroll") for (int n = 0; n < 2; ++n) _Pragma("unroll") for (int k = 0; k < 2; ++k) \
;         acc[ai][bj][m][n] = __builtin_amdgcn_mfma_f32_16x16x32_bf16(Bt[n][k], At[m][k], acc[ai][bj][m][n], 0, 0, 0); __builtin_amdgcn_s_setprio(0); } while (0)
; #define PG8_WAIT_V(n) asm volatile("s_waitcnt vmcnt(" #n ")" ::: "memory")
; #define PG8_WAIT_L(n) asm volatile("s_waitcnt lgkmcnt(" #n ")" ::: "memory")
; #define PG8_BAR __builtin_amdgcn_s_barrier()
; #define PG8_SCHED __builtin_amdgcn_sched_barrier(0)
; template <class Epi, class Sched, bool ALIGN_EPI = false, bool SP2 = false>
; __device__ __forceinline__ void gemm_phase(PG8_LAS unsigned char* lds, const Gemm g, const Sched& S, const Epi& E, const int tid_arg) {
;     ...
;             PG8_LDA(At, 1, 1); PG8_STAGE(PG8_SB(1, 0), b3, voffB); PG8_STAGE(PG8_SB(1, 1), b3 + hstep, voffB); PG8_STAGE(PG8_SA(1, 0), a3, voffA);
;             PG8_WAIT_V(8); PG8_WAIT_L(0); PG8_BAR; PG8_MMA(1, 0, At, B0); PG8_MMA(1, 1, At, B1); PG8_BAR; PG8_SCHED;
;     ...
;         if constexpr (ALIGN_EPI) { if (wr == 0) PG8_BAR; }
	s_add_i32 s44, s62, s50
	v_lshl_add_u64 v[194:195], v[194:195], 0, s[76:77]
	s_mov_b32 m0, s44
	ds_read_b128 v[210:213], v178 offset:49152
	ds_read_b128 v[214:217], v178 offset:50176
	ds_read_b128 v[218:221], v178 offset:51200
	ds_read_b128 v[222:225], v178 offset:52224
	ds_read_b128 v[226:229], v178 offset:53248
	ds_read_b128 v[230:233], v178 offset:54272
	ds_read_b128 v[234:237], v178 offset:55296
	ds_read_b128 v[238:241], v178 offset:56320
	global_load_lds_dwordx4 v[194:195], off
	s_add_i32 m0, s44, 0x2000
	s_add_u32 s42, s42, 0x40080
	v_lshl_add_u64 v[194:195], v[242:243], 0, s[76:77]
	s_addc_u32 s43, s43, 0
	s_add_i32 s44, s63, s50
	global_load_lds_dwordx4 v[194:195], off
	v_lshl_add_u64 v[194:195], s[42:43], 0, v[2:3]
	s_mov_b32 m0, s44
	s_nop 0
	global_load_lds_dwordx4 v[194:195], off
	v_lshl_add_u64 v[194:195], s[42:43], 0, v[146:147]
	s_add_i32 m0, s44, 0x2000
	s_nop 0
	global_load_lds_dwordx4 v[194:195], off
	v_lshl_add_u64 v[194:195], v[244:245], 0, s[76:77]
	s_mov_b32 m0, s56
	s_nop 0
	global_load_lds_dwordx4 v[194:195], off
	v_lshl_add_u64 v[194:195], v[246:247], 0, s[76:77]
	s_mov_b32 m0, s57
	s_nop 0
	global_load_lds_dwordx4 v[194:195], off
	s_waitcnt vmcnt(8)
	s_waitcnt lgkmcnt(0)
	s_barrier
	s_setprio 1
	s_waitcnt lgkmcnt(0)
	v_mfma_f32_16x16x32_bf16 v[64:67], v[132:135], v[210:213], v[64:67]
	v_mfma_f32_16x16x32_bf16 v[60:63], v[156:159], v[210:213], v[60:63]
	v_mfma_f32_16x16x32_bf16 v[48:51], v[132:135], v[218:221], v[48:51]
	v_mfma_f32_16x16x32_bf16 v[44:47], v[156:159], v[218:221], v[44:47]
	v_mfma_f32_16x16x32_bf16 v[32:35], v[132:135], v[226:229], v[32:35]
	v_mfma_f32_16x16x32_bf16 v[28:31], v[156:159], v[226:229], v[28:31]
	v_mfma_f32_16x16x32_bf16 v[16:19], v[132:135], v[234:237], v[16:19]
	v_mfma_f32_16x16x32_bf16 v[12:15], v[156:159], v[234:237], v[12:15]
	v_mfma_f32_16x16x32_bf16 v[64:67], v[136:139], v[214:217], v[64:67]
	v_mfma_f32_16x16x32_bf16 v[60:63], v[160:163], v[214:217], v[60:63]
	v_mfma_f32_16x16x32_bf16 v[48:51], v[136:139], v[222:225], v[48:51]
	v_mfma_f32_16x16x32_bf16 v[44:47], v[160:163], v[222:225], v[44:47]
	v_mfma_f32_16x16x32_bf16 v[32:35], v[136:139], v[230:233], v[32:35]
	v_mfma_f32_16x16x32_bf16 v[28:31], v[160:163], v[230:233], v[28:31]
	v_mfma_f32_16x16x32_bf16 v[16:19], v[136:139], v[238:241], v[16:19]
	v_mfma_f32_16x16x32_bf16 v[12:15], v[160:163], v[238:241], v[12:15]
	s_setprio 0
	s_setprio 1
	v_mfma_f32_16x16x32_bf16 v[56:59], v[164:167], v[210:213], v[56:59]
	v_mfma_f32_16x16x32_bf16 v[52:55], v[186:189], v[210:213], v[52:55]
	v_mfma_f32_16x16x32_bf16 v[40:43], v[164:167], v[218:221], v[40:43]
	v_mfma_f32_16x16x32_bf16 v[36:39], v[186:189], v[218:221], v[36:39]
	v_mfma_f32_16x16x32_bf16 v[24:27], v[164:167], v[226:229], v[24:27]
	v_mfma_f32_16x16x32_bf16 v[20:23], v[186:189], v[226:229], v[20:23]
	v_mfma_f32_16x16x32_bf16 v[8:11], v[164:167], v[234:237], v[8:11]
	v_mfma_f32_16x16x32_bf16 v[4:7], v[186:189], v[234:237], v[4:7]
	v_mfma_f32_16x16x32_bf16 v[56:59], v[182:185], v[214:217], v[56:59]
	v_mfma_f32_16x16x32_bf16 v[52:55], v[190:193], v[214:217], v[52:55]
	v_mfma_f32_16x16x32_bf16 v[40:43], v[182:185], v[222:225], v[40:43]
	v_mfma_f32_16x16x32_bf16 v[36:39], v[190:193], v[222:225], v[36:39]
	v_mfma_f32_16x16x32_bf16 v[24:27], v[182:185], v[230:233], v[24:27]
	v_mfma_f32_16x16x32_bf16 v[20:23], v[190:193], v[230:233], v[20:23]
	v_mfma_f32_16x16x32_bf16 v[8:11], v[182:185], v[238:241], v[8:11]
	v_mfma_f32_16x16x32_bf16 v[4:7], v[190:193], v[238:241], v[4:7]
	s_setprio 0
	s_barrier
	s_add_i32 s61, s61, 2
	s_add_u32 s16, s16, 0x100
	s_addc_u32 s17, s17, 0
	s_add_u32 s59, s59, 0x100
	s_addc_u32 s60, s60, 0
	s_cmp_gt_u32 s61, 13
	s_cbranch_scc0 .LBB0_868
	s_and_b64 vcc, exec, s[28:29]
	s_cbranch_vccz .LBB0_871
	s_barrier

; template <class Epi, class Sched, bool ALIGN_EPI = false, bool SP2 = false>
; __device__ __forceinline__ void gemm_phase(PG8_LAS unsigned char* lds, const Gemm g, const Sched& S, const Epi& E, const int tid_arg) {
;     ...
;         const bool has_next = S.next(ui + 1, nxt);
;         const char* nA = has_next ? (const char*)g.A + (size_t)nxt.pm * tstep : cA; const char* nB = has_next ? (const char*)g.Bt + (size_t)nxt.pn * tstep : cB;
;         for (int t = 0; t < nt; t += 2) {
;             const bool last = (t == nt - 2);
;             const char* a1 = cA + (size_t)(t + 1) * kstep;
;             const char* a2 = last ? nA : cA + (size_t)(t + 2) * kstep; const char* b2 = last ? nB : cB + (size_t)(t + 2) * kstep;
;             const char* a3 = a2 + kstep; const char* b3 = b2 + kstep;
;     ...
; #pragma unroll
;         for (int a = 0; a < 2; ++a)
; #pragma unroll
;             for (int b = 0; b < 2; ++b)
; #pragma unroll
;                 for (int m = 0; m < 4; ++m)
; #pragma unroll
;                     for (int n = 0; n < 2; ++n) acc[a][b][m][n] = (f32x4){0.f, 0.f, 0.f, 0.f};
;         cur = nxt; cA = nA; cB = nB; ++ui;
.LBB0_1079:
	s_ashr_i32 s21, s20, 31
	s_lshl_b64 s[22:23], s[20:21], 19
	s_add_u32 s22, s0, s22
	s_addc_u32 s23, s1, s23
	s_and_b64 s[24:25], s[10:11], exec
	s_cselect_b32 s21, s23, s29
	s_cselect_b32 s47, s22, s28
	s_ashr_i32 s17, s16, 31
	s_lshl_b64 s[24:25], s[16:17], 19
	s_add_u32 s24, s2, s24
	s_addc_u32 s25, s3, s25
	s_and_b64 s[34:35], s[10:11], exec
	s_cselect_b32 s17, s25, s31
	s_cselect_b32 s48, s24, s30
	s_add_u32 s28, s28, 0x40080
	s_addc_u32 s29, s29, 0
	s_add_u32 s49, s30, 0x100
	v_mov_b32_e32 v2, 0
	s_addc_u32 s50, s31, 0
	s_mov_b32 s51, -2
	v_mov_b32_e32 v3, v2
	v_mov_b32_e32 v4, v2
	v_mov_b32_e32 v5, v2
	v_mov_b32_e32 v6, v2
	v_mov_b32_e32 v7, v2
	v_mov_b32_e32 v8, v2
	v_mov_b32_e32 v9, v2
	v_mov_b32_e32 v18, v2
	v_mov_b32_e32 v19, v2
	v_mov_b32_e32 v20, v2
	v_mov_b32_e32 v21, v2
	v_mov_b32_e32 v22, v2
	v_mov_b32_e32 v23, v2
	v_mov_b32_e32 v24, v2
	v_mov_b32_e32 v25, v2
	v_mov_b32_e32 v34, v2
	v_mov_b32_e32 v35, v2
	v_mov_b32_e32 v36, v2
	v_mov_b32_e32 v37, v2
	v_mov_b32_e32 v38, v2
	v_mov_b32_e32 v39, v2
	v_mov_b32_e32 v40, v2
	v_mov_b32_e32 v41, v2
	v_mov_b32_e32 v50, v2
	v_mov_b32_e32 v51, v2
	v_mov_b32_e32 v52, v2
	v_mov_b32_e32 v53, v2
	v_mov_b32_e32 v54, v2
	v_mov_b32_e32 v55, v2
	v_mov_b32_e32 v56, v2
	v_mov_b32_e32 v57, v2
	v_mov_b32_e32 v10, v2
	v_mov_b32_e32 v11, v2
	v_mov_b32_e32 v12, v2
	v_mov_b32_e32 v13, v2
	v_mov_b32_e32 v14, v2
	v_mov_b32_e32 v15, v2
	v_mov_b32_e32 v16, v2
	v_mov_b32_e32 v17, v2
	v_mov_b32_e32 v26, v2
	v_mov_b32_e32 v27, v2
	v_mov_b32_e32 v28, v2
	v_mov_b32_e32 v29, v2
	v_mov_b32_e32 v30, v2
	v_mov_b32_e32 v31, v2
	v_mov_b32_e32 v32, v2
	v_mov_b32_e32 v33, v2
	v_mov_b32_e32 v42, v2
	v_mov_b32_e32 v43, v2
	v_mov_b32_e32 v44, v2
	v_mov_b32_e32 v45, v2
	v_mov_b32_e32 v46, v2
	v_mov_b32_e32 v47, v2
	v_mov_b32_e32 v48, v2
	v_mov_b32_e32 v49, v2
	v_mov_b32_e32 v58, v2
	v_mov_b32_e32 v59, v2
	v_mov_b32_e32 v60, v2
	v_mov_b32_e32 v61, v2
	v_mov_b32_e32 v62, v2
	v_mov_b32_e32 v63, v2
	v_mov_b32_e32 v64, v2
	v_mov_b32_e32 v65, v2
	v_mov_b32_e32 v66, v2
	v_mov_b32_e32 v67, v2
	v_mov_b32_e32 v68, v2
	v_mov_b32_e32 v69, v2
	v_mov_b32_e32 v70, v2
	v_mov_b32_e32 v71, v2
	v_mov_b32_e32 v72, v2
	v_mov_b32_e32 v73, v2
	v_mov_b32_e32 v82, v2
	v_mov_b32_e32 v83, v2
	v_mov_b32_e32 v84, v2
	v_mov_b32_e32 v85, v2
	v_mov_b32_e32 v86, v2
	v_mov_b32_e32 v87, v2
	v_mov_b32_e32 v88, v2
	v_mov_b32_e32 v89, v2
	v_mov_b32_e32 v98, v2
	v_mov_b32_e32 v99, v2
	v_mov_b32_e32 v100, v2
	v_mov_b32_e32 v101, v2
	v_mov_b32_e32 v102, v2
	v_mov_b32_e32 v103, v2
	v_mov_b32_e32 v104, v2
	v_mov_b32_e32 v105, v2
	v_mov_b32_e32 v114, v2
	v_mov_b32_e32 v115, v2
	v_mov_b32_e32 v116, v2
	v_mov_b32_e32 v117, v2
	v_mov_b32_e32 v118, v2
	v_mov_b32_e32 v119, v2
	v_mov_b32_e32 v120, v2
	v_mov_b32_e32 v121, v2
	v_mov_b32_e32 v74, v2
	v_mov_b32_e32 v75, v2
	v_mov_b32_e32 v76, v2
	v_mov_b32_e32 v77, v2
	v_mov_b32_e32 v78, v2
	v_mov_b32_e32 v79, v2
	v_mov_b32_e32 v80, v2
	v_mov_b32_e32 v81, v2
	v_mov_b32_e32 v90, v2
	v_mov_b32_e32 v91, v2
	v_mov_b32_e32 v92, v2
	v_mov_b32_e32 v93, v2
	v_mov_b32_e32 v94, v2
	v_mov_b32_e32 v95, v2
	v_mov_b32_e32 v96, v2
	v_mov_b32_e32 v97, v2
	v_mov_b32_e32 v106, v2
	v_mov_b32_e32 v107, v2
	v_mov_b32_e32 v108, v2
	v_mov_b32_e32 v109, v2
	v_mov_b32_e32 v110, v2
	v_mov_b32_e32 v111, v2
	v_mov_b32_e32 v112, v2
	v_mov_b32_e32 v113, v2
	v_mov_b32_e32 v122, v2
	v_mov_b32_e32 v123, v2
	v_mov_b32_e32 v124, v2
	v_mov_b32_e32 v125, v2
	v_mov_b32_e32 v126, v2
	v_mov_b32_e32 v127, v2
	v_mov_b32_e32 v128, v2
	v_mov_b32_e32 v129, v2
	.p2align 6
	s_nop 0
	s_nop 0
	s_nop 0
	s_nop 0
	s_nop 0
	s_nop 0
	s_nop 0
	s_nop 0
	s_nop 0
	s_nop 0
	s_nop 0

; template <class Epi, class Sched, bool ALIGN_EPI = false, bool SP2 = false>
; __device__ __forceinline__ void gemm_phase(PG8_LAS unsigned char* lds, const Gemm g, const Sched& S, const Epi& E, const int tid_arg) {
;     ...
; #pragma unroll
;         for (int a = 0; a < 2; ++a)
; #pragma unroll
;             for (int b = 0; b < 2; ++b)
; #pragma unroll
;                 for (int m = 0; m < 4; ++m)
; #pragma unroll
;                     for (int n = 0; n < 2; ++n) acc[a][b][m][n] = (f32x4){0.f, 0.f, 0.f, 0.f};
;         cur = nxt; cA = nA; cB = nB; ++ui;
.LBB0_1169:
	s_add_u32 s23, s26, 0x100
	v_mov_b32_e32 v0, 0
	s_addc_u32 s46, s27, 0
	s_mov_b32 s47, -2
	v_mov_b32_e32 v1, v0
	v_mov_b32_e32 v2, v0
	v_mov_b32_e32 v3, v0
	v_mov_b32_e32 v4, v0
	v_mov_b32_e32 v5, v0
	v_mov_b32_e32 v6, v0
	v_mov_b32_e32 v7, v0
	v_mov_b32_e32 v16, v0
	v_mov_b32_e32 v17, v0
	v_mov_b32_e32 v18, v0
	v_mov_b32_e32 v19, v0
	v_mov_b32_e32 v20, v0
	v_mov_b32_e32 v21, v0
	v_mov_b32_e32 v22, v0
	v_mov_b32_e32 v23, v0
	v_mov_b32_e32 v32, v0
	v_mov_b32_e32 v33, v0
	v_mov_b32_e32 v34, v0
	v_mov_b32_e32 v35, v0
	v_mov_b32_e32 v36, v0
	v_mov_b32_e32 v37, v0
	v_mov_b32_e32 v38, v0
	v_mov_b32_e32 v39, v0
	v_mov_b32_e32 v48, v0
	v_mov_b32_e32 v49, v0
	v_mov_b32_e32 v50, v0
	v_mov_b32_e32 v51, v0
	v_mov_b32_e32 v52, v0
	v_mov_b32_e32 v53, v0
	v_mov_b32_e32 v54, v0
	v_mov_b32_e32 v55, v0
	v_mov_b32_e32 v8, v0
	v_mov_b32_e32 v9, v0
	v_mov_b32_e32 v10, v0
	v_mov_b32_e32 v11, v0
	v_mov_b32_e32 v12, v0
	v_mov_b32_e32 v13, v0
	v_mov_b32_e32 v14, v0
	v_mov_b32_e32 v15, v0
	v_mov_b32_e32 v24, v0
	v_mov_b32_e32 v25, v0
	v_mov_b32_e32 v26, v0
	v_mov_b32_e32 v27, v0
	v_mov_b32_e32 v28, v0
	v_mov_b32_e32 v29, v0
	v_mov_b32_e32 v30, v0
	v_mov_b32_e32 v31, v0
	v_mov_b32_e32 v40, v0
	v_mov_b32_e32 v41, v0
	v_mov_b32_e32 v42, v0
	v_mov_b32_e32 v43, v0
	v_mov_b32_e32 v44, v0
	v_mov_b32_e32 v45, v0
	v_mov_b32_e32 v46, v0
	v_mov_b32_e32 v47, v0
	v_mov_b32_e32 v56, v0
	v_mov_b32_e32 v57, v0
	v_mov_b32_e32 v58, v0
	v_mov_b32_e32 v59, v0
	v_mov_b32_e32 v60, v0
	v_mov_b32_e32 v61, v0
	v_mov_b32_e32 v62, v0
	v_mov_b32_e32 v63, v0
	v_mov_b32_e32 v64, v0
	v_mov_b32_e32 v65, v0
	v_mov_b32_e32 v66, v0
	v_mov_b32_e32 v67, v0
	v_mov_b32_e32 v68, v0
	v_mov_b32_e32 v69, v0
	v_mov_b32_e32 v70, v0
	v_mov_b32_e32 v71, v0
	v_mov_b32_e32 v80, v0
	v_mov_b32_e32 v81, v0
	v_mov_b32_e32 v82, v0
	v_mov_b32_e32 v83, v0
	v_mov_b32_e32 v84, v0
	v_mov_b32_e32 v85, v0
	v_mov_b32_e32 v86, v0
	v_mov_b32_e32 v87, v0
	v_mov_b32_e32 v96, v0
	v_mov_b32_e32 v97, v0
	v_mov_b32_e32 v98, v0
	v_mov_b32_e32 v99, v0
	v_mov_b32_e32 v100, v0
	v_mov_b32_e32 v101, v0
	v_mov_b32_e32 v102, v0
	v_mov_b32_e32 v103, v0
	v_mov_b32_e32 v112, v0
	v_mov_b32_e32 v113, v0
	v_mov_b32_e32 v114, v0
	v_mov_b32_e32 v115, v0
	v_mov_b32_e32 v116, v0
	v_mov_b32_e32 v117, v0
	v_mov_b32_e32 v118, v0
	v_mov_b32_e32 v119, v0
	v_mov_b32_e32 v72, v0
	v_mov_b32_e32 v73, v0
	v_mov_b32_e32 v74, v0
	v_mov_b32_e32 v75, v0
	v_mov_b32_e32 v76, v0
	v_mov_b32_e32 v77, v0
	v_mov_b32_e32 v78, v0
	v_mov_b32_e32 v79, v0
	v_mov_b32_e32 v88, v0
	v_mov_b32_e32 v89, v0
	v_mov_b32_e32 v90, v0
	v_mov_b32_e32 v91, v0
	v_mov_b32_e32 v92, v0
	v_mov_b32_e32 v93, v0
	v_mov_b32_e32 v94, v0
	v_mov_b32_e32 v95, v0
	v_mov_b32_e32 v104, v0
	v_mov_b32_e32 v105, v0
	v_mov_b32_e32 v106, v0
	v_mov_b32_e32 v107, v0
	v_mov_b32_e32 v108, v0
	v_mov_b32_e32 v109, v0
	v_mov_b32_e32 v110, v0
	v_mov_b32_e32 v111, v0
	v_mov_b32_e32 v120, v0
	v_mov_b32_e32 v121, v0
	v_mov_b32_e32 v122, v0
	v_mov_b32_e32 v123, v0
	v_mov_b32_e32 v124, v0
	v_mov_b32_e32 v125, v0
	v_mov_b32_e32 v126, v0
	v_mov_b32_e32 v127, v0
	.p2align 6
	s_nop 0
	s_nop 0
	s_nop 0
	s_nop 0
	s_nop 0
	s_nop 0
	s_nop 0
	s_nop 0
	s_nop 0
	s_nop 0
	s_nop 0
